# GEMM K-loops: LDS fragment-read base addresses hoisted (one per-tile base + immediates instead of 4 VALU adds per iteration)
# baseline (speedup 1.0000x reference)
; #define PG8_STAGE(bufoff, gbase, voff) do { _Pragma("unroll") for (int _i = 0; _i < 2; ++_i) \
;         __builtin_amdgcn_global_load_lds((const unsigned*)((const char*)(gbase) + (voff)[_i]), (PG8_LAS unsigned*)(lds + (bufoff) + ldsw + _i * 8192), 16, 0, 0); } while (0)
; #define PG8_LDA(dst, b, h) do { _Pragma("unroll") for (int m = 0; m < 4; ++m) _Pragma("unroll") for (int k = 0; k < 2; ++k) dst[m][k] = *(const PG8_LAS bf16x8*)(lds + PG8_SA(b, h) + aoff + m * 2048 + k * 1024); } while (0)
; #define PG8_LDB(dst, b, h) do { _Pragma("unroll") for (int n = 0; n < 2; ++n) _Pragma("unroll") for (int k = 0; k < 2; ++k) dst[n][k] = *(const PG8_LAS bf16x8*)(lds + PG8_SB(b, h) + boff + n * 2048 + k * 1024); } while (0)
; #define PG8_SCHED __builtin_amdgcn_sched_barrier(0)
; template <class Epi, class Sched, bool ALIGN_EPI = false, bool SP2 = false, bool F16 = false>
; __device__ __forceinline__ void gemm_phase(PG8_LAS unsigned char* lds, const Gemm g, const Sched& S, const Epi& E) {
;     ...
;     for (;;) {
;         const bool has_next = S.next(ui + 1, nxt);
;         const char* nA = has_next ? (const char*)g.A + (size_t)nxt.pm * tstep : cA; const char* nB = has_next ? (const char*)g.Bt + (size_t)nxt.pn * tstep + (nxt.pm >= g.mhalf ? g.bstride : (size_t)0) : cB;
;         for (int t = 0; t < nt; t += 2) {
;             if constexpr (Epi::KHOOK) { if (t == 4 || t == 10) E.khook(acc, cur, t, wr, fr); }
;             const bool last = (t == nt - 2);
;             const char* a1 = cA + (size_t)(t + 1) * kstep;
;             const char* a2 = last ? nA : cA + (size_t)(t + 2) * kstep; const char* b2 = last ? nB : cB + (size_t)(t + 2) * kstep;
;             const char* a3 = a2 + kstep; const char* b3 = b2 + kstep;
;             if (last && has_next) S.a_ready(nxt);
;             if constexpr (SP2) {
;             PG8_LDB(B0, 0, 0); PG8_LDB(B1, 0, 1); PG8_SCHED; PG8_LDA(At, 0, 0); PG8_STAGE(PG8_SA(1, 1), a1 + hstep, voffA);
;     ...
; #pragma unroll
;         for (int a = 0; a < 2; ++a)
; #pragma unroll
;             for (int b = 0; b < 2; ++b)
; #pragma unroll
;                 for (int m = 0; m < 4; ++m)
; #pragma unroll
;                     for (int n = 0; n < 2; ++n) acc[a][b][m][n] = (f32x4){0.f, 0.f, 0.f, 0.f};
;         cur = nxt; cA = nA; cB = nB; ++ui;
.LBB0_255:
	s_ashr_i32 s29, s28, 31
	s_lshl_b64 s[4:5], s[28:29], 19
	s_add_u32 s46, s96, s4
	s_addc_u32 s47, s97, s5
	s_and_b64 s[4:5], s[40:41], exec
	s_cselect_b32 s4, s47, s1
	s_cselect_b32 s5, s46, s0
	s_ashr_i32 s73, s72, 31
	s_lshl_b64 s[54:55], s[72:73], 19
	s_add_u32 s7, s30, s54
	s_addc_u32 s34, s31, s55
	s_cmp_gt_i32 s28, 63
	s_cselect_b32 s54, 0x400000, 0
	s_add_u32 s64, s7, s54
	s_addc_u32 s65, s34, 0
	s_and_b64 s[54:55], s[40:41], exec
	s_cselect_b32 s7, s65, s43
	s_cselect_b32 s34, s64, s42
	s_add_u32 s0, s0, 0x40080
	s_addc_u32 s1, s1, 0
	s_add_u32 s59, s42, 0x100
	v_mov_b32_e32 v0, 0
	s_addc_u32 s61, s43, 0
	s_mov_b32 s67, -2
	v_mov_b32_e32 v1, v0
	v_mov_b32_e32 v2, v0
	v_mov_b32_e32 v3, v0
	v_mov_b32_e32 v4, v0
	v_mov_b32_e32 v5, v0
	v_mov_b32_e32 v6, v0
	v_mov_b32_e32 v7, v0
	v_mov_b32_e32 v8, v0
	v_mov_b32_e32 v9, v0
	v_mov_b32_e32 v10, v0
	v_mov_b32_e32 v11, v0
	v_mov_b32_e32 v12, v0
	v_mov_b32_e32 v13, v0
	v_mov_b32_e32 v14, v0
	v_mov_b32_e32 v15, v0
	v_mov_b32_e32 v16, v0
	v_mov_b32_e32 v17, v0
	v_mov_b32_e32 v18, v0
	v_mov_b32_e32 v19, v0
	v_mov_b32_e32 v20, v0
	v_mov_b32_e32 v21, v0
	v_mov_b32_e32 v22, v0
	v_mov_b32_e32 v23, v0
	v_mov_b32_e32 v24, v0
	v_mov_b32_e32 v25, v0
	v_mov_b32_e32 v26, v0
	v_mov_b32_e32 v27, v0
	v_mov_b32_e32 v28, v0
	v_mov_b32_e32 v29, v0
	v_mov_b32_e32 v30, v0
	v_mov_b32_e32 v31, v0
	v_mov_b32_e32 v64, v0
	v_mov_b32_e32 v65, v0
	v_mov_b32_e32 v66, v0
	v_mov_b32_e32 v67, v0
	v_mov_b32_e32 v68, v0
	v_mov_b32_e32 v69, v0
	v_mov_b32_e32 v70, v0
	v_mov_b32_e32 v71, v0
	v_mov_b32_e32 v72, v0
	v_mov_b32_e32 v73, v0
	v_mov_b32_e32 v74, v0
	v_mov_b32_e32 v75, v0
	v_mov_b32_e32 v76, v0
	v_mov_b32_e32 v77, v0
	v_mov_b32_e32 v78, v0
	v_mov_b32_e32 v79, v0
	s_waitcnt vmcnt(0)
	v_mov_b32_e32 v80, v0
	v_mov_b32_e32 v81, v0
	v_mov_b32_e32 v82, v0
	v_mov_b32_e32 v83, v0
	v_mov_b32_e32 v84, v0
	v_mov_b32_e32 v85, v0
	v_mov_b32_e32 v86, v0
	v_mov_b32_e32 v87, v0
	v_mov_b32_e32 v88, v0
	v_mov_b32_e32 v89, v0
	v_mov_b32_e32 v90, v0
	v_mov_b32_e32 v91, v0
	v_mov_b32_e32 v92, v0
	v_mov_b32_e32 v93, v0
	v_mov_b32_e32 v94, v0
	v_mov_b32_e32 v95, v0
	v_mov_b32_e32 v32, v0
	v_mov_b32_e32 v33, v0
	v_mov_b32_e32 v34, v0
	v_mov_b32_e32 v35, v0
	v_mov_b32_e32 v36, v0
	v_mov_b32_e32 v37, v0
	v_mov_b32_e32 v38, v0
	v_mov_b32_e32 v39, v0
	v_mov_b32_e32 v40, v0
	v_mov_b32_e32 v41, v0
	v_mov_b32_e32 v42, v0
	v_mov_b32_e32 v43, v0
	v_mov_b32_e32 v44, v0
	v_mov_b32_e32 v45, v0
	v_mov_b32_e32 v46, v0
	v_mov_b32_e32 v47, v0
	v_mov_b32_e32 v48, v0
	v_mov_b32_e32 v49, v0
	v_mov_b32_e32 v50, v0
	v_mov_b32_e32 v51, v0
	v_mov_b32_e32 v52, v0
	v_mov_b32_e32 v53, v0
	v_mov_b32_e32 v54, v0
	v_mov_b32_e32 v55, v0
	v_mov_b32_e32 v56, v0
	v_mov_b32_e32 v57, v0
	v_mov_b32_e32 v58, v0
	v_mov_b32_e32 v59, v0
	v_mov_b32_e32 v60, v0
	v_mov_b32_e32 v61, v0
	v_mov_b32_e32 v62, v0
	v_mov_b32_e32 v63, v0
	v_mov_b32_e32 v96, v0
	v_mov_b32_e32 v97, v0
	v_mov_b32_e32 v98, v0
	v_mov_b32_e32 v99, v0
	v_mov_b32_e32 v100, v0
	v_mov_b32_e32 v101, v0
	v_mov_b32_e32 v102, v0
	v_mov_b32_e32 v103, v0
	v_mov_b32_e32 v104, v0
	v_mov_b32_e32 v105, v0
	v_mov_b32_e32 v106, v0
	v_mov_b32_e32 v107, v0
	v_mov_b32_e32 v108, v0
	v_mov_b32_e32 v109, v0
	v_mov_b32_e32 v110, v0
	v_mov_b32_e32 v111, v0
	v_mov_b32_e32 v112, v0
	v_mov_b32_e32 v113, v0
	v_mov_b32_e32 v114, v0
	v_mov_b32_e32 v115, v0
	v_mov_b32_e32 v116, v0
	v_mov_b32_e32 v117, v0
	v_mov_b32_e32 v118, v0
	v_mov_b32_e32 v119, v0
	v_mov_b32_e32 v120, v0
	v_mov_b32_e32 v121, v0
	v_mov_b32_e32 v122, v0
	v_mov_b32_e32 v123, v0
	v_mov_b32_e32 v124, v0
	v_mov_b32_e32 v125, v0
	v_mov_b32_e32 v126, v0
	v_mov_b32_e32 v127, v0
	v_add_u32_e32 v242, 0x10000, v239
.LBB0_256:
	s_add_u32 s42, s0, 0xfffc0080
	s_addc_u32 s43, s1, -1
	s_add_i32 s68, 0, 0x10000
	s_cmp_eq_u32 s67, 12
	s_cselect_b32 s55, s4, s43
	s_cselect_b32 s54, s5, s42
	s_cselect_b32 s43, s7, s61
	s_cselect_b32 s42, s34, s59
	s_add_i32 s70, 0, 0x14000
	ds_read_b128 v[130:133], v242
	ds_read_b128 v[134:137], v242 offset:1024
	ds_read_b128 v[138:141], v242 offset:2048
	ds_read_b128 v[162:165], v242 offset:3072
	ds_read_b128 v[166:169], v242 offset:16384
	ds_read_b128 v[170:173], v242 offset:17408
	ds_read_b128 v[186:189], v242 offset:18432
	ds_read_b128 v[190:193], v242 offset:19456
	s_add_i32 m0, s21, 0xc000
	ds_read_b128 v[194:197], v240
	ds_read_b128 v[198:201], v240 offset:1024
	ds_read_b128 v[202:205], v240 offset:2048
	ds_read_b128 v[206:209], v240 offset:3072
	ds_read_b128 v[210:213], v240 offset:4096
	ds_read_b128 v[214:217], v240 offset:5120
	ds_read_b128 v[218:221], v240 offset:6144
	ds_read_b128 v[222:225], v240 offset:7168
	global_load_lds_dwordx4 v154, s[0:1]
	s_add_i32 m0, s21, 0xe000
	s_nop 0
	global_load_lds_dwordx4 v156, s[0:1]
	s_waitcnt vmcnt(8)
	s_waitcnt lgkmcnt(0)
	s_barrier
; #define PG8_STAGE(bufoff, gbase, voff) do { _Pragma("unroll") for (int _i = 0; _i < 2; ++_i) \
;         __builtin_amdgcn_global_load_lds((const unsigned*)((const char*)(gbase) + (voff)[_i]), (PG8_LAS unsigned*)(lds + (bufoff) + ldsw + _i * 8192), 16, 0, 0); } while (0)
; #define PG8_LDA(dst, b, h) do { _Pragma("unroll") for (int m = 0; m < 4; ++m) _Pragma("unroll") for (int k = 0; k < 2; ++k) dst[m][k] = *(const PG8_LAS bf16x8*)(lds + PG8_SA(b, h) + aoff + m * 2048 + k * 1024); } while (0)
; #define PG8_LDB(dst, b, h) do { _Pragma("unroll") for (int n = 0; n < 2; ++n) _Pragma("unroll") for (int k = 0; k < 2; ++k) dst[n][k] = *(const PG8_LAS bf16x8*)(lds + PG8_SB(b, h) + boff + n * 2048 + k * 1024); } while (0)
; #define PG8_MMA(ai, bj, At, Bt) do { __builtin_amdgcn_s_setprio(1); _Pragma("unroll") for (int m = 0; m < 4; ++m) _Pragma("unroll") for (int n = 0; n < 2; ++n) _Pragma("unroll") for (int k = 0; k < 2; ++k) \
;         acc[ai][bj][m][n] = mma16<F16>(Bt[n][k], At[m][k], acc[ai][bj][m][n]); __builtin_amdgcn_s_setprio(0); } while (0)
; #define PG8_WAIT_V(n) asm volatile("s_waitcnt vmcnt(" #n ")" ::: "memory")
; #define PG8_WAIT_L(n) asm volatile("s_waitcnt lgkmcnt(" #n ")" ::: "memory")
; #define PG8_BAR __builtin_amdgcn_s_barrier()
; #define PG8_SCHED __builtin_amdgcn_sched_barrier(0)
; template <class Epi, class Sched, bool ALIGN_EPI = false, bool SP2 = false, bool F16 = false>
; __device__ __forceinline__ void gemm_phase(PG8_LAS unsigned char* lds, const Gemm g, const Sched& S, const Epi& E) {
;     ...
;             PG8_LDB(B0, 0, 0); PG8_LDB(B1, 0, 1); PG8_SCHED; PG8_LDA(At, 0, 0); PG8_STAGE(PG8_SA(1, 1), a1 + hstep, voffA);
;             PG8_WAIT_V(8); PG8_WAIT_L(0); PG8_BAR; PG8_MMA(0, 0, At, B0); PG8_MMA(0, 1, At, B1); PG8_BAR; PG8_SCHED;
;             PG8_LDA(At, 0, 1); PG8_STAGE(PG8_SB(0, 0), b2, voffB); PG8_STAGE(PG8_SB(0, 1), b2 + hstep, voffB); PG8_STAGE(PG8_SA(0, 0), a2, voffA);
;             PG8_WAIT_V(8); PG8_WAIT_L(0); PG8_BAR; PG8_MMA(1, 0, At, B0); PG8_MMA(1, 1, At, B1); PG8_BAR; PG8_SCHED;
	s_setprio 1
	s_waitcnt lgkmcnt(0)
	v_mfma_f32_16x16x32_f16 v[124:127], v[130:133], v[194:197], v[124:127]
	v_mfma_f32_16x16x32_f16 v[120:123], v[138:141], v[194:197], v[120:123]
	v_mfma_f32_16x16x32_f16 v[116:119], v[130:133], v[202:205], v[116:119]
	v_mfma_f32_16x16x32_f16 v[112:115], v[138:141], v[202:205], v[112:115]
	v_mfma_f32_16x16x32_f16 v[108:111], v[130:133], v[210:213], v[108:111]
	v_mfma_f32_16x16x32_f16 v[104:107], v[138:141], v[210:213], v[104:107]
	v_mfma_f32_16x16x32_f16 v[100:103], v[130:133], v[218:221], v[100:103]
	v_mfma_f32_16x16x32_f16 v[96:99], v[138:141], v[218:221], v[96:99]
	v_mfma_f32_16x16x32_f16 v[124:127], v[134:137], v[198:201], v[124:127]
	v_mfma_f32_16x16x32_f16 v[120:123], v[162:165], v[198:201], v[120:123]
	v_mfma_f32_16x16x32_f16 v[116:119], v[134:137], v[206:209], v[116:119]
	v_mfma_f32_16x16x32_f16 v[112:115], v[162:165], v[206:209], v[112:115]
	v_mfma_f32_16x16x32_f16 v[108:111], v[134:137], v[214:217], v[108:111]
	v_mfma_f32_16x16x32_f16 v[104:107], v[162:165], v[214:217], v[104:107]
	v_mfma_f32_16x16x32_f16 v[100:103], v[134:137], v[222:225], v[100:103]
	v_mfma_f32_16x16x32_f16 v[96:99], v[162:165], v[222:225], v[96:99]
	s_setprio 0
	s_setprio 1
	v_mfma_f32_16x16x32_f16 v[60:63], v[166:169], v[194:197], v[60:63]
	v_mfma_f32_16x16x32_f16 v[56:59], v[186:189], v[194:197], v[56:59]
	v_mfma_f32_16x16x32_f16 v[52:55], v[166:169], v[202:205], v[52:55]
	v_mfma_f32_16x16x32_f16 v[48:51], v[186:189], v[202:205], v[48:51]
	v_mfma_f32_16x16x32_f16 v[44:47], v[166:169], v[210:213], v[44:47]
	v_mfma_f32_16x16x32_f16 v[40:43], v[186:189], v[210:213], v[40:43]
	v_mfma_f32_16x16x32_f16 v[36:39], v[166:169], v[218:221], v[36:39]
	v_mfma_f32_16x16x32_f16 v[32:35], v[186:189], v[218:221], v[32:35]
	v_mfma_f32_16x16x32_f16 v[60:63], v[170:173], v[198:201], v[60:63]
	v_mfma_f32_16x16x32_f16 v[56:59], v[190:193], v[198:201], v[56:59]
	v_mfma_f32_16x16x32_f16 v[52:55], v[170:173], v[206:209], v[52:55]
	v_mfma_f32_16x16x32_f16 v[48:51], v[190:193], v[206:209], v[48:51]
	v_mfma_f32_16x16x32_f16 v[44:47], v[170:173], v[214:217], v[44:47]
	v_mfma_f32_16x16x32_f16 v[40:43], v[190:193], v[214:217], v[40:43]
	v_mfma_f32_16x16x32_f16 v[36:39], v[170:173], v[222:225], v[36:39]
	v_mfma_f32_16x16x32_f16 v[32:35], v[190:193], v[222:225], v[32:35]
	s_setprio 0
	s_barrier
	s_add_u32 s98, s42, s16
	s_addc_u32 s99, s43, s17
	s_add_u32 s100, s54, s16
	s_addc_u32 s101, s55, s17
	s_add_i32 s68, s68, s20
	s_mov_b32 m0, s68
	ds_read_b128 v[194:197], v240 offset:16384
	ds_read_b128 v[198:201], v240 offset:17408
	ds_read_b128 v[202:205], v240 offset:18432
	ds_read_b128 v[206:209], v240 offset:19456
	ds_read_b128 v[210:213], v240 offset:20480
	ds_read_b128 v[214:217], v240 offset:21504
	ds_read_b128 v[218:221], v240 offset:22528
	ds_read_b128 v[222:225], v240 offset:23552
	global_load_lds_dwordx4 v146, s[42:43]
	s_add_i32 m0, s68, 0x2000
	s_add_u32 s68, s42, 0x40000
	s_addc_u32 s69, s43, 0
	s_add_i32 s70, s70, s20
	global_load_lds_dwordx4 v142, s[42:43]
	s_mov_b32 m0, s70
	s_nop 0
	global_load_lds_dwordx4 v146, s[68:69]
	s_add_i32 m0, s70, 0x2000
	s_nop 0
	global_load_lds_dwordx4 v142, s[68:69]
	s_mov_b32 m0, s21
	s_nop 0
	global_load_lds_dwordx4 v148, s[54:55]
	s_mov_b32 m0, s14
	s_nop 0
	global_load_lds_dwordx4 v144, s[54:55]
	s_waitcnt vmcnt(8)
	s_waitcnt lgkmcnt(0)
	s_barrier
	s_setprio 1
	s_waitcnt lgkmcnt(0)
	v_mfma_f32_16x16x32_f16 v[92:95], v[130:133], v[194:197], v[92:95]
	v_mfma_f32_16x16x32_f16 v[88:91], v[138:141], v[194:197], v[88:91]
	v_mfma_f32_16x16x32_f16 v[84:87], v[130:133], v[202:205], v[84:87]
	v_mfma_f32_16x16x32_f16 v[80:83], v[138:141], v[202:205], v[80:83]
	v_mfma_f32_16x16x32_f16 v[76:79], v[130:133], v[210:213], v[76:79]
	v_mfma_f32_16x16x32_f16 v[72:75], v[138:141], v[210:213], v[72:75]
	v_mfma_f32_16x16x32_f16 v[68:71], v[130:133], v[218:221], v[68:71]
	v_mfma_f32_16x16x32_f16 v[64:67], v[138:141], v[218:221], v[64:67]
	v_mfma_f32_16x16x32_f16 v[92:95], v[134:137], v[198:201], v[92:95]
	v_mfma_f32_16x16x32_f16 v[88:91], v[162:165], v[198:201], v[88:91]
	v_mfma_f32_16x16x32_f16 v[84:87], v[134:137], v[206:209], v[84:87]
	v_mfma_f32_16x16x32_f16 v[80:83], v[162:165], v[206:209], v[80:83]
	v_mfma_f32_16x16x32_f16 v[76:79], v[134:137], v[214:217], v[76:79]
	v_mfma_f32_16x16x32_f16 v[72:75], v[162:165], v[214:217], v[72:75]
	v_mfma_f32_16x16x32_f16 v[68:71], v[134:137], v[222:225], v[68:71]
	v_mfma_f32_16x16x32_f16 v[64:67], v[162:165], v[222:225], v[64:67]
	s_setprio 0
	s_setprio 1
	v_mfma_f32_16x16x32_f16 v[28:31], v[166:169], v[194:197], v[28:31]
	v_mfma_f32_16x16x32_f16 v[24:27], v[186:189], v[194:197], v[24:27]
	v_mfma_f32_16x16x32_f16 v[20:23], v[166:169], v[202:205], v[20:23]
	v_mfma_f32_16x16x32_f16 v[16:19], v[186:189], v[202:205], v[16:19]
	v_mfma_f32_16x16x32_f16 v[12:15], v[166:169], v[210:213], v[12:15]
	v_mfma_f32_16x16x32_f16 v[8:11], v[186:189], v[210:213], v[8:11]
	v_mfma_f32_16x16x32_f16 v[4:7], v[166:169], v[218:221], v[4:7]
	v_mfma_f32_16x16x32_f16 v[0:3], v[186:189], v[218:221], v[0:3]
	v_mfma_f32_16x16x32_f16 v[28:31], v[170:173], v[198:201], v[28:31]
	v_mfma_f32_16x16x32_f16 v[24:27], v[190:193], v[198:201], v[24:27]
	v_mfma_f32_16x16x32_f16 v[20:23], v[170:173], v[206:209], v[20:23]
	v_mfma_f32_16x16x32_f16 v[16:19], v[190:193], v[206:209], v[16:19]
	v_mfma_f32_16x16x32_f16 v[12:15], v[170:173], v[214:217], v[12:15]
	v_mfma_f32_16x16x32_f16 v[8:11], v[190:193], v[214:217], v[8:11]
	v_mfma_f32_16x16x32_f16 v[4:7], v[170:173], v[222:225], v[4:7]
	v_mfma_f32_16x16x32_f16 v[0:3], v[190:193], v[222:225], v[0:3]
	s_setprio 0
	s_barrier
; #define PG8_STAGE(bufoff, gbase, voff) do { _Pragma("unroll") for (int _i = 0; _i < 2; ++_i) \
;         __builtin_amdgcn_global_load_lds((const unsigned*)((const char*)(gbase) + (voff)[_i]), (PG8_LAS unsigned*)(lds + (bufoff) + ldsw + _i * 8192), 16, 0, 0); } while (0)
; #define PG8_LDA(dst, b, h) do { _Pragma("unroll") for (int m = 0; m < 4; ++m) _Pragma("unroll") for (int k = 0; k < 2; ++k) dst[m][k] = *(const PG8_LAS bf16x8*)(lds + PG8_SA(b, h) + aoff + m * 2048 + k * 1024); } while (0)
; #define PG8_LDB(dst, b, h) do { _Pragma("unroll") for (int n = 0; n < 2; ++n) _Pragma("unroll") for (int k = 0; k < 2; ++k) dst[n][k] = *(const PG8_LAS bf16x8*)(lds + PG8_SB(b, h) + boff + n * 2048 + k * 1024); } while (0)
; #define PG8_MMA(ai, bj, At, Bt) do { __builtin_amdgcn_s_setprio(1); _Pragma("unroll") for (int m = 0; m < 4; ++m) _Pragma("unroll") for (int n = 0; n < 2; ++n) _Pragma("unroll") for (int k = 0; k < 2; ++k) \
;         acc[ai][bj][m][n] = mma16<F16>(Bt[n][k], At[m][k], acc[ai][bj][m][n]); __builtin_amdgcn_s_setprio(0); } while (0)
; #define PG8_WAIT_V(n) asm volatile("s_waitcnt vmcnt(" #n ")" ::: "memory")
; #define PG8_WAIT_L(n) asm volatile("s_waitcnt lgkmcnt(" #n ")" ::: "memory")
; #define PG8_BAR __builtin_amdgcn_s_barrier()
; #define PG8_SCHED __builtin_amdgcn_sched_barrier(0)
; template <class Epi, class Sched, bool ALIGN_EPI = false, bool SP2 = false, bool F16 = false>
; __device__ __forceinline__ void gemm_phase(PG8_LAS unsigned char* lds, const Gemm g, const Sched& S, const Epi& E) {
;     ...
;             PG8_LDB(B0, 1, 0); PG8_LDB(B1, 1, 1); PG8_SCHED; PG8_LDA(At, 1, 0); PG8_STAGE(PG8_SA(0, 1), a2 + hstep, voffA);
;             PG8_WAIT_V(8); PG8_WAIT_L(0); PG8_BAR; PG8_MMA(0, 0, At, B0); PG8_MMA(0, 1, At, B1); PG8_BAR; PG8_SCHED;
;             PG8_LDA(At, 1, 1); PG8_STAGE(PG8_SB(1, 0), b3, voffB); PG8_STAGE(PG8_SB(1, 1), b3 + hstep, voffB); PG8_STAGE(PG8_SA(1, 0), a3, voffA);
;             PG8_WAIT_V(8); PG8_WAIT_L(0); PG8_BAR; PG8_MMA(1, 0, At, B0); PG8_MMA(1, 1, At, B1); PG8_BAR; PG8_SCHED;
	s_add_i32 s68, 0, 0x18000
	s_add_i32 s69, 0, 0x1c000
	ds_read_b128 v[130:133], v242 offset:32768
	ds_read_b128 v[134:137], v242 offset:33792
	ds_read_b128 v[138:141], v242 offset:34816
	ds_read_b128 v[162:165], v242 offset:35840
	ds_read_b128 v[166:169], v242 offset:49152
	ds_read_b128 v[170:173], v242 offset:50176
	ds_read_b128 v[186:189], v242 offset:51200
	ds_read_b128 v[190:193], v242 offset:52224
	s_add_u32 s54, s54, 0x40000
	s_addc_u32 s55, s55, 0
	s_mov_b32 m0, s15
	ds_read_b128 v[194:197], v240 offset:32768
	ds_read_b128 v[198:201], v240 offset:33792
	ds_read_b128 v[202:205], v240 offset:34816
	ds_read_b128 v[206:209], v240 offset:35840
	ds_read_b128 v[210:213], v240 offset:36864
	ds_read_b128 v[214:217], v240 offset:37888
	ds_read_b128 v[218:221], v240 offset:38912
	ds_read_b128 v[222:225], v240 offset:39936
	global_load_lds_dwordx4 v148, s[54:55]
	s_mov_b32 m0, s37
	s_nop 0
	global_load_lds_dwordx4 v144, s[54:55]
	s_waitcnt vmcnt(8)
	s_waitcnt lgkmcnt(0)
	s_barrier
	s_setprio 1
	s_waitcnt lgkmcnt(0)
	v_mfma_f32_16x16x32_f16 v[124:127], v[130:133], v[194:197], v[124:127]
	v_mfma_f32_16x16x32_f16 v[120:123], v[138:141], v[194:197], v[120:123]
	v_mfma_f32_16x16x32_f16 v[116:119], v[130:133], v[202:205], v[116:119]
	v_mfma_f32_16x16x32_f16 v[112:115], v[138:141], v[202:205], v[112:115]
	v_mfma_f32_16x16x32_f16 v[108:111], v[130:133], v[210:213], v[108:111]
	v_mfma_f32_16x16x32_f16 v[104:107], v[138:141], v[210:213], v[104:107]
	v_mfma_f32_16x16x32_f16 v[100:103], v[130:133], v[218:221], v[100:103]
	v_mfma_f32_16x16x32_f16 v[96:99], v[138:141], v[218:221], v[96:99]
	v_mfma_f32_16x16x32_f16 v[124:127], v[134:137], v[198:201], v[124:127]
	v_mfma_f32_16x16x32_f16 v[120:123], v[162:165], v[198:201], v[120:123]
	v_mfma_f32_16x16x32_f16 v[116:119], v[134:137], v[206:209], v[116:119]
	v_mfma_f32_16x16x32_f16 v[112:115], v[162:165], v[206:209], v[112:115]
	v_mfma_f32_16x16x32_f16 v[108:111], v[134:137], v[214:217], v[108:111]
	v_mfma_f32_16x16x32_f16 v[104:107], v[162:165], v[214:217], v[104:107]
	v_mfma_f32_16x16x32_f16 v[100:103], v[134:137], v[222:225], v[100:103]
	v_mfma_f32_16x16x32_f16 v[96:99], v[162:165], v[222:225], v[96:99]
	s_setprio 0
	s_setprio 1
	v_mfma_f32_16x16x32_f16 v[60:63], v[166:169], v[194:197], v[60:63]
	v_mfma_f32_16x16x32_f16 v[56:59], v[186:189], v[194:197], v[56:59]
	v_mfma_f32_16x16x32_f16 v[52:55], v[166:169], v[202:205], v[52:55]
	v_mfma_f32_16x16x32_f16 v[48:51], v[186:189], v[202:205], v[48:51]
	v_mfma_f32_16x16x32_f16 v[44:47], v[166:169], v[210:213], v[44:47]
	v_mfma_f32_16x16x32_f16 v[40:43], v[186:189], v[210:213], v[40:43]
	v_mfma_f32_16x16x32_f16 v[36:39], v[166:169], v[218:221], v[36:39]
	v_mfma_f32_16x16x32_f16 v[32:35], v[186:189], v[218:221], v[32:35]
	v_mfma_f32_16x16x32_f16 v[60:63], v[170:173], v[198:201], v[60:63]
	v_mfma_f32_16x16x32_f16 v[56:59], v[190:193], v[198:201], v[56:59]
	v_mfma_f32_16x16x32_f16 v[52:55], v[170:173], v[206:209], v[52:55]
	v_mfma_f32_16x16x32_f16 v[48:51], v[190:193], v[206:209], v[48:51]
	v_mfma_f32_16x16x32_f16 v[44:47], v[170:173], v[214:217], v[44:47]
	v_mfma_f32_16x16x32_f16 v[40:43], v[190:193], v[214:217], v[40:43]
	v_mfma_f32_16x16x32_f16 v[36:39], v[170:173], v[222:225], v[36:39]
	v_mfma_f32_16x16x32_f16 v[32:35], v[190:193], v[222:225], v[32:35]
	s_setprio 0
	s_barrier
	s_add_i32 s54, s68, s20
	s_mov_b32 m0, s54
	ds_read_b128 v[194:197], v240 offset:49152
	ds_read_b128 v[198:201], v240 offset:50176
	ds_read_b128 v[202:205], v240 offset:51200
	ds_read_b128 v[206:209], v240 offset:52224
	ds_read_b128 v[210:213], v240 offset:53248
	ds_read_b128 v[214:217], v240 offset:54272
	ds_read_b128 v[218:221], v240 offset:55296
	ds_read_b128 v[222:225], v240 offset:56320
	global_load_lds_dwordx4 v146, s[98:99]
	s_add_i32 m0, s54, 0x2000
	s_add_u32 s42, s42, 0x40080
	s_addc_u32 s43, s43, 0
	s_add_i32 s54, s69, s20
	global_load_lds_dwordx4 v142, s[98:99]
	s_mov_b32 m0, s54
	s_nop 0
	global_load_lds_dwordx4 v146, s[42:43]
	s_add_i32 m0, s54, 0x2000
	s_nop 0
	global_load_lds_dwordx4 v142, s[42:43]
	s_mov_b32 m0, s44
	s_nop 0
	global_load_lds_dwordx4 v148, s[100:101]
	s_mov_b32 m0, s45
	s_nop 0
	global_load_lds_dwordx4 v144, s[100:101]
	s_waitcnt vmcnt(8)
	s_waitcnt lgkmcnt(0)
	s_barrier
	s_setprio 1
	s_waitcnt lgkmcnt(0)
	v_mfma_f32_16x16x32_f16 v[92:95], v[130:133], v[194:197], v[92:95]
	v_mfma_f32_16x16x32_f16 v[88:91], v[138:141], v[194:197], v[88:91]
	v_mfma_f32_16x16x32_f16 v[84:87], v[130:133], v[202:205], v[84:87]
	v_mfma_f32_16x16x32_f16 v[80:83], v[138:141], v[202:205], v[80:83]
	v_mfma_f32_16x16x32_f16 v[76:79], v[130:133], v[210:213], v[76:79]
	v_mfma_f32_16x16x32_f16 v[72:75], v[138:141], v[210:213], v[72:75]
	v_mfma_f32_16x16x32_f16 v[68:71], v[130:133], v[218:221], v[68:71]
	v_mfma_f32_16x16x32_f16 v[64:67], v[138:141], v[218:221], v[64:67]
	v_mfma_f32_16x16x32_f16 v[92:95], v[134:137], v[198:201], v[92:95]
	v_mfma_f32_16x16x32_f16 v[88:91], v[162:165], v[198:201], v[88:91]
	v_mfma_f32_16x16x32_f16 v[84:87], v[134:137], v[206:209], v[84:87]
	v_mfma_f32_16x16x32_f16 v[80:83], v[162:165], v[206:209], v[80:83]
	v_mfma_f32_16x16x32_f16 v[76:79], v[134:137], v[214:217], v[76:79]
	v_mfma_f32_16x16x32_f16 v[72:75], v[162:165], v[214:217], v[72:75]
	v_mfma_f32_16x16x32_f16 v[68:71], v[134:137], v[222:225], v[68:71]
	v_mfma_f32_16x16x32_f16 v[64:67], v[162:165], v[222:225], v[64:67]
	s_setprio 0
	s_setprio 1
	v_mfma_f32_16x16x32_f16 v[28:31], v[166:169], v[194:197], v[28:31]
	v_mfma_f32_16x16x32_f16 v[24:27], v[186:189], v[194:197], v[24:27]
	v_mfma_f32_16x16x32_f16 v[20:23], v[166:169], v[202:205], v[20:23]
	v_mfma_f32_16x16x32_f16 v[16:19], v[186:189], v[202:205], v[16:19]
	v_mfma_f32_16x16x32_f16 v[12:15], v[166:169], v[210:213], v[12:15]
	v_mfma_f32_16x16x32_f16 v[8:11], v[186:189], v[210:213], v[8:11]
	v_mfma_f32_16x16x32_f16 v[4:7], v[166:169], v[218:221], v[4:7]
	v_mfma_f32_16x16x32_f16 v[0:3], v[186:189], v[218:221], v[0:3]
	v_mfma_f32_16x16x32_f16 v[28:31], v[170:173], v[198:201], v[28:31]
	v_mfma_f32_16x16x32_f16 v[24:27], v[190:193], v[198:201], v[24:27]
	v_mfma_f32_16x16x32_f16 v[20:23], v[170:173], v[206:209], v[20:23]
	v_mfma_f32_16x16x32_f16 v[16:19], v[190:193], v[206:209], v[16:19]
	v_mfma_f32_16x16x32_f16 v[12:15], v[170:173], v[214:217], v[12:15]
	v_mfma_f32_16x16x32_f16 v[8:11], v[190:193], v[214:217], v[8:11]
	v_mfma_f32_16x16x32_f16 v[4:7], v[170:173], v[222:225], v[4:7]
	v_mfma_f32_16x16x32_f16 v[0:3], v[190:193], v[222:225], v[0:3]
	s_setprio 0
	s_barrier
	s_add_i32 s67, s67, 2
	s_add_u32 s0, s0, 0x100
	s_addc_u32 s1, s1, 0
	s_add_u32 s59, s59, 0x100
	s_addc_u32 s61, s61, 0
	s_cmp_gt_u32 s67, 13
	s_cbranch_scc0 .LBB0_256
	s_and_b64 vcc, exec, s[8:9]
	s_cbranch_vccz .LBB0_259
	s_barrier

; #define PG8_STAGE(bufoff, gbase, voff) do { _Pragma("unroll") for (int _i = 0; _i < 2; ++_i) \
;         __builtin_amdgcn_global_load_lds((const unsigned*)((const char*)(gbase) + (voff)[_i]), (PG8_LAS unsigned*)(lds + (bufoff) + ldsw + _i * 8192), 16, 0, 0); } while (0)
; #define PG8_LDA(dst, b, h) do { _Pragma("unroll") for (int m = 0; m < 4; ++m) _Pragma("unroll") for (int k = 0; k < 2; ++k) dst[m][k] = *(const PG8_LAS bf16x8*)(lds + PG8_SA(b, h) + aoff + m * 2048 + k * 1024); } while (0)
; #define PG8_LDB(dst, b, h) do { _Pragma("unroll") for (int n = 0; n < 2; ++n) _Pragma("unroll") for (int k = 0; k < 2; ++k) dst[n][k] = *(const PG8_LAS bf16x8*)(lds + PG8_SB(b, h) + boff + n * 2048 + k * 1024); } while (0)
; #define PG8_SCHED __builtin_amdgcn_sched_barrier(0)
; template <class Epi, class Sched, bool ALIGN_EPI = false, bool SP2 = false, bool F16 = false>
; __device__ __forceinline__ void gemm_phase(PG8_LAS unsigned char* lds, const Gemm g, const Sched& S, const Epi& E) {
;     ...
;     for (;;) {
;         const bool has_next = S.next(ui + 1, nxt);
;         const char* nA = has_next ? (const char*)g.A + (size_t)nxt.pm * tstep : cA; const char* nB = has_next ? (const char*)g.Bt + (size_t)nxt.pn * tstep + (nxt.pm >= g.mhalf ? g.bstride : (size_t)0) : cB;
;         for (int t = 0; t < nt; t += 2) {
;             if constexpr (Epi::KHOOK) { if (t == 4 || t == 10) E.khook(acc, cur, t, wr, fr); }
;             const bool last = (t == nt - 2);
;             const char* a1 = cA + (size_t)(t + 1) * kstep;
;             const char* a2 = last ? nA : cA + (size_t)(t + 2) * kstep; const char* b2 = last ? nB : cB + (size_t)(t + 2) * kstep;
;             const char* a3 = a2 + kstep; const char* b3 = b2 + kstep;
;             if (last && has_next) S.a_ready(nxt);
;             if constexpr (SP2) {
;             PG8_LDB(B0, 0, 0); PG8_LDB(B1, 0, 1); PG8_SCHED; PG8_LDA(At, 0, 0); PG8_STAGE(PG8_SA(1, 1), a1 + hstep, voffA);
;     ...
; #pragma unroll
;         for (int a = 0; a < 2; ++a)
; #pragma unroll
;             for (int b = 0; b < 2; ++b)
; #pragma unroll
;                 for (int m = 0; m < 4; ++m)
; #pragma unroll
;                     for (int n = 0; n < 2; ++n) acc[a][b][m][n] = (f32x4){0.f, 0.f, 0.f, 0.f};
;         cur = nxt; cA = nA; cB = nB; ++ui;
.LBB0_903:
	s_ashr_i32 s49, s48, 31
	s_lshl_b64 s[4:5], s[48:49], 19
	s_add_u32 s50, s96, s4
	s_addc_u32 s51, s97, s5
	s_and_b64 s[4:5], s[40:41], exec
	s_cselect_b32 s4, s51, s55
	s_cselect_b32 s5, s50, s54
	s_ashr_i32 s47, s46, 31
	s_lshl_b64 s[52:53], s[46:47], 19
	s_add_u32 s37, s6, s52
	s_addc_u32 s47, s7, s53
	s_cmp_gt_i32 s48, 63
	s_cselect_b32 s49, 0xb00000, 0
	s_add_u32 s52, s37, s49
	s_addc_u32 s53, s47, 0
	s_and_b64 s[58:59], s[40:41], exec
	s_cselect_b32 s37, s53, s57
	s_cselect_b32 s47, s52, s56
	s_add_u32 s54, s54, 0x40080
	s_addc_u32 s55, s55, 0
	s_add_u32 s49, s56, 0x100
	v_mov_b32_e32 v0, 0
	s_addc_u32 s60, s57, 0
	s_mov_b32 s61, -2
	v_mov_b32_e32 v1, v0
	v_mov_b32_e32 v2, v0
	v_mov_b32_e32 v3, v0
	v_mov_b32_e32 v4, v0
	v_mov_b32_e32 v5, v0
	v_mov_b32_e32 v6, v0
	v_mov_b32_e32 v7, v0
	v_mov_b32_e32 v16, v0
	v_mov_b32_e32 v17, v0
	v_mov_b32_e32 v18, v0
	v_mov_b32_e32 v19, v0
	v_mov_b32_e32 v20, v0
	v_mov_b32_e32 v21, v0
	v_mov_b32_e32 v22, v0
	v_mov_b32_e32 v23, v0
	v_mov_b32_e32 v48, v0
	v_mov_b32_e32 v49, v0
	v_mov_b32_e32 v50, v0
	v_mov_b32_e32 v51, v0
	v_mov_b32_e32 v52, v0
	v_mov_b32_e32 v53, v0
	v_mov_b32_e32 v54, v0
	v_mov_b32_e32 v55, v0
	v_mov_b32_e32 v64, v0
	v_mov_b32_e32 v65, v0
	v_mov_b32_e32 v66, v0
	v_mov_b32_e32 v67, v0
	v_mov_b32_e32 v68, v0
	v_mov_b32_e32 v69, v0
	v_mov_b32_e32 v70, v0
	v_mov_b32_e32 v71, v0
	v_mov_b32_e32 v8, v0
	v_mov_b32_e32 v9, v0
	v_mov_b32_e32 v10, v0
	v_mov_b32_e32 v11, v0
	v_mov_b32_e32 v12, v0
	v_mov_b32_e32 v13, v0
	v_mov_b32_e32 v14, v0
	v_mov_b32_e32 v15, v0
	v_mov_b32_e32 v24, v0
	v_mov_b32_e32 v25, v0
	v_mov_b32_e32 v26, v0
	v_mov_b32_e32 v27, v0
	v_mov_b32_e32 v28, v0
	v_mov_b32_e32 v29, v0
	v_mov_b32_e32 v30, v0
	v_mov_b32_e32 v31, v0
	v_mov_b32_e32 v56, v0
	v_mov_b32_e32 v57, v0
	v_mov_b32_e32 v58, v0
	v_mov_b32_e32 v59, v0
	v_mov_b32_e32 v60, v0
	v_mov_b32_e32 v61, v0
	v_mov_b32_e32 v62, v0
	v_mov_b32_e32 v63, v0
	v_mov_b32_e32 v72, v0
	v_mov_b32_e32 v73, v0
	v_mov_b32_e32 v74, v0
	v_mov_b32_e32 v75, v0
	v_mov_b32_e32 v76, v0
	v_mov_b32_e32 v77, v0
	v_mov_b32_e32 v78, v0
	v_mov_b32_e32 v79, v0
	s_waitcnt vmcnt(0)
	v_mov_b32_e32 v80, v0
	v_mov_b32_e32 v81, v0
	v_mov_b32_e32 v82, v0
	v_mov_b32_e32 v83, v0
	v_mov_b32_e32 v84, v0
	v_mov_b32_e32 v85, v0
	v_mov_b32_e32 v86, v0
	v_mov_b32_e32 v87, v0
	v_mov_b32_e32 v96, v0
	v_mov_b32_e32 v97, v0
	v_mov_b32_e32 v98, v0
	v_mov_b32_e32 v99, v0
	v_mov_b32_e32 v100, v0
	v_mov_b32_e32 v101, v0
	v_mov_b32_e32 v102, v0
	v_mov_b32_e32 v103, v0
	v_mov_b32_e32 v112, v0
	v_mov_b32_e32 v113, v0
	v_mov_b32_e32 v114, v0
	v_mov_b32_e32 v115, v0
	v_mov_b32_e32 v116, v0
	v_mov_b32_e32 v117, v0
	v_mov_b32_e32 v118, v0
	v_mov_b32_e32 v119, v0
	v_mov_b32_e32 v130, v0
	v_mov_b32_e32 v131, v0
	v_mov_b32_e32 v132, v0
	v_mov_b32_e32 v133, v0
	v_mov_b32_e32 v134, v0
	v_mov_b32_e32 v135, v0
	v_mov_b32_e32 v136, v0
	v_mov_b32_e32 v137, v0
	v_mov_b32_e32 v88, v0
	v_mov_b32_e32 v89, v0
	v_mov_b32_e32 v90, v0
	v_mov_b32_e32 v91, v0
	v_mov_b32_e32 v92, v0
	v_mov_b32_e32 v93, v0
	v_mov_b32_e32 v94, v0
	v_mov_b32_e32 v95, v0
	v_mov_b32_e32 v104, v0
	v_mov_b32_e32 v105, v0
	v_mov_b32_e32 v106, v0
	v_mov_b32_e32 v107, v0
	v_mov_b32_e32 v108, v0
	v_mov_b32_e32 v109, v0
	v_mov_b32_e32 v110, v0
	v_mov_b32_e32 v111, v0
	v_mov_b32_e32 v120, v0
	v_mov_b32_e32 v121, v0
	v_mov_b32_e32 v122, v0
	v_mov_b32_e32 v123, v0
	v_mov_b32_e32 v124, v0
	v_mov_b32_e32 v125, v0
	v_mov_b32_e32 v126, v0
	v_mov_b32_e32 v127, v0
	v_mov_b32_e32 v138, v0
	v_mov_b32_e32 v139, v0
	v_mov_b32_e32 v140, v0
	v_mov_b32_e32 v141, v0
	v_mov_b32_e32 v142, v0
	v_mov_b32_e32 v143, v0
	v_mov_b32_e32 v144, v0
	v_mov_b32_e32 v145, v0
	v_add_u32_e32 v172, 0x10000, v163
.LBB0_904:
	s_add_u32 s56, s54, 0xfffc0080
	s_addc_u32 s57, s55, -1
	s_add_i32 s62, 0, 0x10000
	s_cmp_eq_u32 s61, 12
	s_cselect_b32 s59, s4, s57
	s_cselect_b32 s58, s5, s56
	s_cselect_b32 s57, s37, s60
	s_cselect_b32 s56, s47, s49
	s_add_i32 s64, 0, 0x14000
	ds_read_b128 v[32:35], v172
	ds_read_b128 v[36:39], v172 offset:1024
	ds_read_b128 v[40:43], v172 offset:2048
	ds_read_b128 v[44:47], v172 offset:3072
	ds_read_b128 v[156:159], v172 offset:16384
	ds_read_b128 v[168:171], v172 offset:17408
	ds_read_b128 v[186:189], v172 offset:18432
	ds_read_b128 v[190:193], v172 offset:19456
	s_add_i32 m0, s9, 0xc000
	ds_read_b128 v[194:197], v165
	ds_read_b128 v[198:201], v165 offset:1024
	ds_read_b128 v[202:205], v165 offset:2048
	ds_read_b128 v[206:209], v165 offset:3072
	ds_read_b128 v[210:213], v165 offset:4096
	ds_read_b128 v[214:217], v165 offset:5120
	ds_read_b128 v[218:221], v165 offset:6144
	ds_read_b128 v[222:225], v165 offset:7168
	global_load_lds_dwordx4 v152, s[54:55]
	s_add_i32 m0, s9, 0xe000
	s_nop 0
	global_load_lds_dwordx4 v154, s[54:55]
	s_waitcnt vmcnt(8)
	s_waitcnt lgkmcnt(0)
	s_barrier
; #define PG8_STAGE(bufoff, gbase, voff) do { _Pragma("unroll") for (int _i = 0; _i < 2; ++_i) \
;         __builtin_amdgcn_global_load_lds((const unsigned*)((const char*)(gbase) + (voff)[_i]), (PG8_LAS unsigned*)(lds + (bufoff) + ldsw + _i * 8192), 16, 0, 0); } while (0)
; #define PG8_LDA(dst, b, h) do { _Pragma("unroll") for (int m = 0; m < 4; ++m) _Pragma("unroll") for (int k = 0; k < 2; ++k) dst[m][k] = *(const PG8_LAS bf16x8*)(lds + PG8_SA(b, h) + aoff + m * 2048 + k * 1024); } while (0)
; #define PG8_LDB(dst, b, h) do { _Pragma("unroll") for (int n = 0; n < 2; ++n) _Pragma("unroll") for (int k = 0; k < 2; ++k) dst[n][k] = *(const PG8_LAS bf16x8*)(lds + PG8_SB(b, h) + boff + n * 2048 + k * 1024); } while (0)
; #define PG8_MMA(ai, bj, At, Bt) do { __builtin_amdgcn_s_setprio(1); _Pragma("unroll") for (int m = 0; m < 4; ++m) _Pragma("unroll") for (int n = 0; n < 2; ++n) _Pragma("unroll") for (int k = 0; k < 2; ++k) \
;         acc[ai][bj][m][n] = mma16<F16>(Bt[n][k], At[m][k], acc[ai][bj][m][n]); __builtin_amdgcn_s_setprio(0); } while (0)
; #define PG8_WAIT_V(n) asm volatile("s_waitcnt vmcnt(" #n ")" ::: "memory")
; #define PG8_WAIT_L(n) asm volatile("s_waitcnt lgkmcnt(" #n ")" ::: "memory")
; #define PG8_BAR __builtin_amdgcn_s_barrier()
; #define PG8_SCHED __builtin_amdgcn_sched_barrier(0)
; template <class Epi, class Sched, bool ALIGN_EPI = false, bool SP2 = false, bool F16 = false>
; __device__ __forceinline__ void gemm_phase(PG8_LAS unsigned char* lds, const Gemm g, const Sched& S, const Epi& E) {
;     ...
;             PG8_LDB(B0, 0, 0); PG8_LDB(B1, 0, 1); PG8_SCHED; PG8_LDA(At, 0, 0); PG8_STAGE(PG8_SA(1, 1), a1 + hstep, voffA);
;             PG8_WAIT_V(8); PG8_WAIT_L(0); PG8_BAR; PG8_MMA(0, 0, At, B0); PG8_MMA(0, 1, At, B1); PG8_BAR; PG8_SCHED;
;             PG8_LDA(At, 0, 1); PG8_STAGE(PG8_SB(0, 0), b2, voffB); PG8_STAGE(PG8_SB(0, 1), b2 + hstep, voffB); PG8_STAGE(PG8_SA(0, 0), a2, voffA);
;             PG8_WAIT_V(8); PG8_WAIT_L(0); PG8_BAR; PG8_MMA(1, 0, At, B0); PG8_MMA(1, 1, At, B1); PG8_BAR; PG8_SCHED;
	s_setprio 1
	s_waitcnt lgkmcnt(0)
	v_mfma_f32_16x16x32_f16 v[142:145], v[32:35], v[194:197], v[142:145]
	v_mfma_f32_16x16x32_f16 v[138:141], v[40:43], v[194:197], v[138:141]
	v_mfma_f32_16x16x32_f16 v[124:127], v[32:35], v[202:205], v[124:127]
	v_mfma_f32_16x16x32_f16 v[120:123], v[40:43], v[202:205], v[120:123]
	v_mfma_f32_16x16x32_f16 v[108:111], v[32:35], v[210:213], v[108:111]
	v_mfma_f32_16x16x32_f16 v[104:107], v[40:43], v[210:213], v[104:107]
	v_mfma_f32_16x16x32_f16 v[92:95], v[32:35], v[218:221], v[92:95]
	v_mfma_f32_16x16x32_f16 v[88:91], v[40:43], v[218:221], v[88:91]
	v_mfma_f32_16x16x32_f16 v[142:145], v[36:39], v[198:201], v[142:145]
	v_mfma_f32_16x16x32_f16 v[138:141], v[44:47], v[198:201], v[138:141]
	v_mfma_f32_16x16x32_f16 v[124:127], v[36:39], v[206:209], v[124:127]
	v_mfma_f32_16x16x32_f16 v[120:123], v[44:47], v[206:209], v[120:123]
	v_mfma_f32_16x16x32_f16 v[108:111], v[36:39], v[214:217], v[108:111]
	v_mfma_f32_16x16x32_f16 v[104:107], v[44:47], v[214:217], v[104:107]
	v_mfma_f32_16x16x32_f16 v[92:95], v[36:39], v[222:225], v[92:95]
	v_mfma_f32_16x16x32_f16 v[88:91], v[44:47], v[222:225], v[88:91]
	s_setprio 0
	s_setprio 1
	v_mfma_f32_16x16x32_f16 v[134:137], v[156:159], v[194:197], v[134:137]
	v_mfma_f32_16x16x32_f16 v[130:133], v[186:189], v[194:197], v[130:133]
	v_mfma_f32_16x16x32_f16 v[116:119], v[156:159], v[202:205], v[116:119]
	v_mfma_f32_16x16x32_f16 v[112:115], v[186:189], v[202:205], v[112:115]
	v_mfma_f32_16x16x32_f16 v[100:103], v[156:159], v[210:213], v[100:103]
	v_mfma_f32_16x16x32_f16 v[96:99], v[186:189], v[210:213], v[96:99]
	v_mfma_f32_16x16x32_f16 v[84:87], v[156:159], v[218:221], v[84:87]
	v_mfma_f32_16x16x32_f16 v[80:83], v[186:189], v[218:221], v[80:83]
	v_mfma_f32_16x16x32_f16 v[134:137], v[168:171], v[198:201], v[134:137]
	v_mfma_f32_16x16x32_f16 v[130:133], v[190:193], v[198:201], v[130:133]
	v_mfma_f32_16x16x32_f16 v[116:119], v[168:171], v[206:209], v[116:119]
	v_mfma_f32_16x16x32_f16 v[112:115], v[190:193], v[206:209], v[112:115]
	v_mfma_f32_16x16x32_f16 v[100:103], v[168:171], v[214:217], v[100:103]
	v_mfma_f32_16x16x32_f16 v[96:99], v[190:193], v[214:217], v[96:99]
	v_mfma_f32_16x16x32_f16 v[84:87], v[168:171], v[222:225], v[84:87]
	v_mfma_f32_16x16x32_f16 v[80:83], v[190:193], v[222:225], v[80:83]
	s_setprio 0
	s_barrier
	s_add_u32 s98, s56, s16
	s_addc_u32 s99, s57, s17
	s_add_u32 s100, s58, s16
	s_addc_u32 s101, s59, s17
	s_add_i32 s62, s62, s8
	s_mov_b32 m0, s62
	ds_read_b128 v[194:197], v165 offset:16384
	ds_read_b128 v[198:201], v165 offset:17408
	ds_read_b128 v[202:205], v165 offset:18432
	ds_read_b128 v[206:209], v165 offset:19456
	ds_read_b128 v[210:213], v165 offset:20480
	ds_read_b128 v[214:217], v165 offset:21504
	ds_read_b128 v[218:221], v165 offset:22528
	ds_read_b128 v[222:225], v165 offset:23552
	global_load_lds_dwordx4 v128, s[56:57]
	s_add_i32 m0, s62, 0x2000
	s_add_u32 s62, s56, 0x40000
	s_addc_u32 s63, s57, 0
	s_add_i32 s64, s64, s8
	global_load_lds_dwordx4 v146, s[56:57]
	s_mov_b32 m0, s64
	s_nop 0
	global_load_lds_dwordx4 v128, s[62:63]
	s_add_i32 m0, s64, 0x2000
	s_nop 0
	global_load_lds_dwordx4 v146, s[62:63]
	s_mov_b32 m0, s9
	s_nop 0
	global_load_lds_dwordx4 v150, s[58:59]
	s_mov_b32 m0, s10
	s_nop 0
	global_load_lds_dwordx4 v148, s[58:59]
	s_waitcnt vmcnt(8)
	s_waitcnt lgkmcnt(0)
	s_barrier
	s_setprio 1
	s_waitcnt lgkmcnt(0)
	v_mfma_f32_16x16x32_f16 v[76:79], v[32:35], v[194:197], v[76:79]
	v_mfma_f32_16x16x32_f16 v[72:75], v[40:43], v[194:197], v[72:75]
	v_mfma_f32_16x16x32_f16 v[60:63], v[32:35], v[202:205], v[60:63]
	v_mfma_f32_16x16x32_f16 v[56:59], v[40:43], v[202:205], v[56:59]
	v_mfma_f32_16x16x32_f16 v[28:31], v[32:35], v[210:213], v[28:31]
	v_mfma_f32_16x16x32_f16 v[24:27], v[40:43], v[210:213], v[24:27]
	v_mfma_f32_16x16x32_f16 v[12:15], v[32:35], v[218:221], v[12:15]
	v_mfma_f32_16x16x32_f16 v[8:11], v[40:43], v[218:221], v[8:11]
	v_mfma_f32_16x16x32_f16 v[76:79], v[36:39], v[198:201], v[76:79]
	v_mfma_f32_16x16x32_f16 v[72:75], v[44:47], v[198:201], v[72:75]
	v_mfma_f32_16x16x32_f16 v[60:63], v[36:39], v[206:209], v[60:63]
	v_mfma_f32_16x16x32_f16 v[56:59], v[44:47], v[206:209], v[56:59]
	v_mfma_f32_16x16x32_f16 v[28:31], v[36:39], v[214:217], v[28:31]
	v_mfma_f32_16x16x32_f16 v[24:27], v[44:47], v[214:217], v[24:27]
	v_mfma_f32_16x16x32_f16 v[12:15], v[36:39], v[222:225], v[12:15]
	v_mfma_f32_16x16x32_f16 v[8:11], v[44:47], v[222:225], v[8:11]
	s_setprio 0
	s_setprio 1
	v_mfma_f32_16x16x32_f16 v[20:23], v[156:159], v[210:213], v[20:23]
	v_mfma_f32_16x16x32_f16 v[16:19], v[186:189], v[210:213], v[16:19]
	v_mfma_f32_16x16x32_f16 v[4:7], v[156:159], v[218:221], v[4:7]
	v_mfma_f32_16x16x32_f16 v[0:3], v[186:189], v[218:221], v[0:3]
	v_mfma_f32_16x16x32_f16 v[32:35], v[156:159], v[194:197], v[68:71]
	v_mfma_f32_16x16x32_f16 v[36:39], v[186:189], v[194:197], v[64:67]
	v_mfma_f32_16x16x32_f16 v[40:43], v[156:159], v[202:205], v[52:55]
	v_mfma_f32_16x16x32_f16 v[44:47], v[186:189], v[202:205], v[48:51]
	v_mfma_f32_16x16x32_f16 v[20:23], v[168:171], v[214:217], v[20:23]
	v_mfma_f32_16x16x32_f16 v[16:19], v[190:193], v[214:217], v[16:19]
	v_mfma_f32_16x16x32_f16 v[4:7], v[168:171], v[222:225], v[4:7]
	v_mfma_f32_16x16x32_f16 v[0:3], v[190:193], v[222:225], v[0:3]
	v_mfma_f32_16x16x32_f16 v[32:35], v[168:171], v[198:201], v[32:35]
	v_mfma_f32_16x16x32_f16 v[36:39], v[190:193], v[198:201], v[36:39]
	v_mfma_f32_16x16x32_f16 v[40:43], v[168:171], v[206:209], v[40:43]
	v_mfma_f32_16x16x32_f16 v[44:47], v[190:193], v[206:209], v[44:47]
	s_setprio 0
	s_barrier
; #define PG8_STAGE(bufoff, gbase, voff) do { _Pragma("unroll") for (int _i = 0; _i < 2; ++_i) \
;         __builtin_amdgcn_global_load_lds((const unsigned*)((const char*)(gbase) + (voff)[_i]), (PG8_LAS unsigned*)(lds + (bufoff) + ldsw + _i * 8192), 16, 0, 0); } while (0)
; #define PG8_LDA(dst, b, h) do { _Pragma("unroll") for (int m = 0; m < 4; ++m) _Pragma("unroll") for (int k = 0; k < 2; ++k) dst[m][k] = *(const PG8_LAS bf16x8*)(lds + PG8_SA(b, h) + aoff + m * 2048 + k * 1024); } while (0)
; #define PG8_LDB(dst, b, h) do { _Pragma("unroll") for (int n = 0; n < 2; ++n) _Pragma("unroll") for (int k = 0; k < 2; ++k) dst[n][k] = *(const PG8_LAS bf16x8*)(lds + PG8_SB(b, h) + boff + n * 2048 + k * 1024); } while (0)
; #define PG8_MMA(ai, bj, At, Bt) do { __builtin_amdgcn_s_setprio(1); _Pragma("unroll") for (int m = 0; m < 4; ++m) _Pragma("unroll") for (int n = 0; n < 2; ++n) _Pragma("unroll") for (int k = 0; k < 2; ++k) \
;         acc[ai][bj][m][n] = mma16<F16>(Bt[n][k], At[m][k], acc[ai][bj][m][n]); __builtin_amdgcn_s_setprio(0); } while (0)
; #define PG8_WAIT_V(n) asm volatile("s_waitcnt vmcnt(" #n ")" ::: "memory")
; #define PG8_WAIT_L(n) asm volatile("s_waitcnt lgkmcnt(" #n ")" ::: "memory")
; #define PG8_BAR __builtin_amdgcn_s_barrier()
; #define PG8_SCHED __builtin_amdgcn_sched_barrier(0)
; template <class Epi, class Sched, bool ALIGN_EPI = false, bool SP2 = false, bool F16 = false>
; __device__ __forceinline__ void gemm_phase(PG8_LAS unsigned char* lds, const Gemm g, const Sched& S, const Epi& E) {
;     ...
;             PG8_LDB(B0, 1, 0); PG8_LDB(B1, 1, 1); PG8_SCHED; PG8_LDA(At, 1, 0); PG8_STAGE(PG8_SA(0, 1), a2 + hstep, voffA);
;             PG8_WAIT_V(8); PG8_WAIT_L(0); PG8_BAR; PG8_MMA(0, 0, At, B0); PG8_MMA(0, 1, At, B1); PG8_BAR; PG8_SCHED;
;             PG8_LDA(At, 1, 1); PG8_STAGE(PG8_SB(1, 0), b3, voffB); PG8_STAGE(PG8_SB(1, 1), b3 + hstep, voffB); PG8_STAGE(PG8_SA(1, 0), a3, voffA);
;             PG8_WAIT_V(8); PG8_WAIT_L(0); PG8_BAR; PG8_MMA(1, 0, At, B0); PG8_MMA(1, 1, At, B1); PG8_BAR; PG8_SCHED;
	s_add_i32 s62, 0, 0x18000
	s_add_i32 s63, 0, 0x1c000
	ds_read_b128 v[48:51], v172 offset:32768
	ds_read_b128 v[52:55], v172 offset:33792
	ds_read_b128 v[64:67], v172 offset:34816
	ds_read_b128 v[68:71], v172 offset:35840
	ds_read_b128 v[156:159], v172 offset:49152
	ds_read_b128 v[168:171], v172 offset:50176
	ds_read_b128 v[186:189], v172 offset:51200
	ds_read_b128 v[190:193], v172 offset:52224
	s_add_u32 s58, s58, 0x40000
	s_addc_u32 s59, s59, 0
	s_mov_b32 m0, s11
	ds_read_b128 v[194:197], v165 offset:32768
	ds_read_b128 v[198:201], v165 offset:33792
	ds_read_b128 v[202:205], v165 offset:34816
	ds_read_b128 v[206:209], v165 offset:35840
	ds_read_b128 v[210:213], v165 offset:36864
	ds_read_b128 v[214:217], v165 offset:37888
	ds_read_b128 v[218:221], v165 offset:38912
	ds_read_b128 v[222:225], v165 offset:39936
	global_load_lds_dwordx4 v150, s[58:59]
	s_mov_b32 m0, s13
	s_nop 0
	global_load_lds_dwordx4 v148, s[58:59]
	s_waitcnt vmcnt(8)
	s_waitcnt lgkmcnt(0)
	s_barrier
	s_setprio 1
	s_waitcnt lgkmcnt(0)
	v_mfma_f32_16x16x32_f16 v[142:145], v[48:51], v[194:197], v[142:145]
	v_mfma_f32_16x16x32_f16 v[138:141], v[64:67], v[194:197], v[138:141]
	v_mfma_f32_16x16x32_f16 v[124:127], v[48:51], v[202:205], v[124:127]
	v_mfma_f32_16x16x32_f16 v[120:123], v[64:67], v[202:205], v[120:123]
	v_mfma_f32_16x16x32_f16 v[108:111], v[48:51], v[210:213], v[108:111]
	v_mfma_f32_16x16x32_f16 v[104:107], v[64:67], v[210:213], v[104:107]
	v_mfma_f32_16x16x32_f16 v[92:95], v[48:51], v[218:221], v[92:95]
	v_mfma_f32_16x16x32_f16 v[88:91], v[64:67], v[218:221], v[88:91]
	v_mfma_f32_16x16x32_f16 v[142:145], v[52:55], v[198:201], v[142:145]
	v_mfma_f32_16x16x32_f16 v[138:141], v[68:71], v[198:201], v[138:141]
	v_mfma_f32_16x16x32_f16 v[124:127], v[52:55], v[206:209], v[124:127]
	v_mfma_f32_16x16x32_f16 v[120:123], v[68:71], v[206:209], v[120:123]
	v_mfma_f32_16x16x32_f16 v[108:111], v[52:55], v[214:217], v[108:111]
	v_mfma_f32_16x16x32_f16 v[104:107], v[68:71], v[214:217], v[104:107]
	v_mfma_f32_16x16x32_f16 v[92:95], v[52:55], v[222:225], v[92:95]
	v_mfma_f32_16x16x32_f16 v[88:91], v[68:71], v[222:225], v[88:91]
	s_setprio 0
	s_setprio 1
	v_mfma_f32_16x16x32_f16 v[134:137], v[156:159], v[194:197], v[134:137]
	v_mfma_f32_16x16x32_f16 v[130:133], v[186:189], v[194:197], v[130:133]
	v_mfma_f32_16x16x32_f16 v[116:119], v[156:159], v[202:205], v[116:119]
	v_mfma_f32_16x16x32_f16 v[112:115], v[186:189], v[202:205], v[112:115]
	v_mfma_f32_16x16x32_f16 v[100:103], v[156:159], v[210:213], v[100:103]
	v_mfma_f32_16x16x32_f16 v[96:99], v[186:189], v[210:213], v[96:99]
	v_mfma_f32_16x16x32_f16 v[84:87], v[156:159], v[218:221], v[84:87]
	v_mfma_f32_16x16x32_f16 v[80:83], v[186:189], v[218:221], v[80:83]
	v_mfma_f32_16x16x32_f16 v[134:137], v[168:171], v[198:201], v[134:137]
	v_mfma_f32_16x16x32_f16 v[130:133], v[190:193], v[198:201], v[130:133]
	v_mfma_f32_16x16x32_f16 v[116:119], v[168:171], v[206:209], v[116:119]
	v_mfma_f32_16x16x32_f16 v[112:115], v[190:193], v[206:209], v[112:115]
	v_mfma_f32_16x16x32_f16 v[100:103], v[168:171], v[214:217], v[100:103]
	v_mfma_f32_16x16x32_f16 v[96:99], v[190:193], v[214:217], v[96:99]
	v_mfma_f32_16x16x32_f16 v[84:87], v[168:171], v[222:225], v[84:87]
	v_mfma_f32_16x16x32_f16 v[80:83], v[190:193], v[222:225], v[80:83]
	s_setprio 0
	s_barrier
	s_add_i32 s58, s62, s8
	s_mov_b32 m0, s58
	ds_read_b128 v[194:197], v165 offset:49152
	ds_read_b128 v[198:201], v165 offset:50176
	ds_read_b128 v[202:205], v165 offset:51200
	ds_read_b128 v[206:209], v165 offset:52224
	ds_read_b128 v[210:213], v165 offset:53248
	ds_read_b128 v[214:217], v165 offset:54272
	ds_read_b128 v[218:221], v165 offset:55296
	ds_read_b128 v[222:225], v165 offset:56320
	global_load_lds_dwordx4 v128, s[98:99]
	s_add_i32 m0, s58, 0x2000
	s_add_u32 s56, s56, 0x40080
	s_addc_u32 s57, s57, 0
	s_add_i32 s58, s63, s8
	global_load_lds_dwordx4 v146, s[98:99]
	s_mov_b32 m0, s58
	s_nop 0
	global_load_lds_dwordx4 v128, s[56:57]
	s_add_i32 m0, s58, 0x2000
	s_nop 0
	global_load_lds_dwordx4 v146, s[56:57]
	s_mov_b32 m0, s20
	s_nop 0
	global_load_lds_dwordx4 v150, s[100:101]
	s_mov_b32 m0, s21
	s_nop 0
	global_load_lds_dwordx4 v148, s[100:101]
	s_waitcnt vmcnt(8)
	s_waitcnt lgkmcnt(0)
	s_barrier
	s_setprio 1
	s_waitcnt lgkmcnt(0)
	v_mfma_f32_16x16x32_f16 v[76:79], v[48:51], v[194:197], v[76:79]
	v_mfma_f32_16x16x32_f16 v[72:75], v[64:67], v[194:197], v[72:75]
	v_mfma_f32_16x16x32_f16 v[60:63], v[48:51], v[202:205], v[60:63]
	v_mfma_f32_16x16x32_f16 v[56:59], v[64:67], v[202:205], v[56:59]
	v_mfma_f32_16x16x32_f16 v[28:31], v[48:51], v[210:213], v[28:31]
	v_mfma_f32_16x16x32_f16 v[24:27], v[64:67], v[210:213], v[24:27]
	v_mfma_f32_16x16x32_f16 v[12:15], v[48:51], v[218:221], v[12:15]
	v_mfma_f32_16x16x32_f16 v[8:11], v[64:67], v[218:221], v[8:11]
	v_mfma_f32_16x16x32_f16 v[76:79], v[52:55], v[198:201], v[76:79]
	v_mfma_f32_16x16x32_f16 v[72:75], v[68:71], v[198:201], v[72:75]
	v_mfma_f32_16x16x32_f16 v[60:63], v[52:55], v[206:209], v[60:63]
	v_mfma_f32_16x16x32_f16 v[56:59], v[68:71], v[206:209], v[56:59]
	v_mfma_f32_16x16x32_f16 v[28:31], v[52:55], v[214:217], v[28:31]
	v_mfma_f32_16x16x32_f16 v[24:27], v[68:71], v[214:217], v[24:27]
	v_mfma_f32_16x16x32_f16 v[12:15], v[52:55], v[222:225], v[12:15]
	v_mfma_f32_16x16x32_f16 v[8:11], v[68:71], v[222:225], v[8:11]
	s_setprio 0
	s_setprio 1
	v_mfma_f32_16x16x32_f16 v[32:35], v[156:159], v[194:197], v[32:35]
	v_mfma_f32_16x16x32_f16 v[68:71], v[168:171], v[198:201], v[32:35]
	v_mfma_f32_16x16x32_f16 v[32:35], v[186:189], v[194:197], v[36:39]
	v_mfma_f32_16x16x32_f16 v[64:67], v[190:193], v[198:201], v[32:35]
	v_mfma_f32_16x16x32_f16 v[32:35], v[156:159], v[202:205], v[40:43]
	v_mfma_f32_16x16x32_f16 v[52:55], v[168:171], v[206:209], v[32:35]
	v_mfma_f32_16x16x32_f16 v[32:35], v[186:189], v[202:205], v[44:47]
	v_mfma_f32_16x16x32_f16 v[20:23], v[156:159], v[210:213], v[20:23]
	v_mfma_f32_16x16x32_f16 v[16:19], v[186:189], v[210:213], v[16:19]
	v_mfma_f32_16x16x32_f16 v[4:7], v[156:159], v[218:221], v[4:7]
	v_mfma_f32_16x16x32_f16 v[0:3], v[186:189], v[218:221], v[0:3]
	v_mfma_f32_16x16x32_f16 v[48:51], v[190:193], v[206:209], v[32:35]
	v_mfma_f32_16x16x32_f16 v[20:23], v[168:171], v[214:217], v[20:23]
	v_mfma_f32_16x16x32_f16 v[16:19], v[190:193], v[214:217], v[16:19]
	v_mfma_f32_16x16x32_f16 v[4:7], v[168:171], v[222:225], v[4:7]
	v_mfma_f32_16x16x32_f16 v[0:3], v[190:193], v[222:225], v[0:3]
	s_setprio 0
	s_barrier
	s_add_i32 s61, s61, 2
	s_add_u32 s54, s54, 0x100
	s_addc_u32 s55, s55, 0
	s_add_u32 s49, s49, 0x100
	s_addc_u32 s60, s60, 0
	s_cmp_gt_u32 s61, 13
	s_cbranch_scc0 .LBB0_904
	s_and_b64 vcc, exec, s[44:45]
	s_cbranch_vccz .LBB0_907
	s_barrier

; #define PG8_STAGE(bufoff, gbase, voff) do { _Pragma("unroll") for (int _i = 0; _i < 2; ++_i) \
;         __builtin_amdgcn_global_load_lds((const unsigned*)((const char*)(gbase) + (voff)[_i]), (PG8_LAS unsigned*)(lds + (bufoff) + ldsw + _i * 8192), 16, 0, 0); } while (0)
; #define PG8_LDA(dst, b, h) do { _Pragma("unroll") for (int m = 0; m < 4; ++m) _Pragma("unroll") for (int k = 0; k < 2; ++k) dst[m][k] = *(const PG8_LAS bf16x8*)(lds + PG8_SA(b, h) + aoff + m * 2048 + k * 1024); } while (0)
; #define PG8_LDB(dst, b, h) do { _Pragma("unroll") for (int n = 0; n < 2; ++n) _Pragma("unroll") for (int k = 0; k < 2; ++k) dst[n][k] = *(const PG8_LAS bf16x8*)(lds + PG8_SB(b, h) + boff + n * 2048 + k * 1024); } while (0)
; #define PG8_MMA(ai, bj, At, Bt) do { __builtin_amdgcn_s_setprio(1); _Pragma("unroll") for (int m = 0; m < 4; ++m) _Pragma("unroll") for (int n = 0; n < 2; ++n) _Pragma("unroll") for (int k = 0; k < 2; ++k) \
;         acc[ai][bj][m][n] = mma16<F16>(Bt[n][k], At[m][k], acc[ai][bj][m][n]); __builtin_amdgcn_s_setprio(0); } while (0)
; #define PG8_BAR __builtin_amdgcn_s_barrier()
; template <class Epi, class Sched, bool ALIGN_EPI = false, bool SP2 = false, bool F16 = false>
; __device__ __forceinline__ void gemm_phase(PG8_LAS unsigned char* lds, const Gemm g, const Sched& S, const Epi& E) {
;     ...
;         for (int t = 0; t < nt; t += 2) {
;             if constexpr (Epi::KHOOK) { if (t == 4 || t == 10) E.khook(acc, cur, t, wr, fr); }
;             const bool last = (t == nt - 2);
;             const char* a1 = cA + (size_t)(t + 1) * kstep;
;             const char* a2 = last ? nA : cA + (size_t)(t + 2) * kstep; const char* b2 = last ? nB : cB + (size_t)(t + 2) * kstep;
;             const char* a3 = a2 + kstep; const char* b3 = b2 + kstep;
;             if (last && has_next) S.a_ready(nxt);
;             if constexpr (SP2) {
;             PG8_LDB(B0, 0, 0); PG8_LDB(B1, 0, 1); PG8_SCHED; PG8_LDA(At, 0, 0); PG8_STAGE(PG8_SA(1, 1), a1 + hstep, voffA);
;             PG8_WAIT_V(8); PG8_WAIT_L(0); PG8_BAR; PG8_MMA(0, 0, At, B0); PG8_MMA(0, 1, At, B1); PG8_BAR; PG8_SCHED;
;     ...
; #pragma unroll
;         for (int a = 0; a < 2; ++a)
; #pragma unroll
;             for (int b = 0; b < 2; ++b)
; #pragma unroll
;                 for (int m = 0; m < 4; ++m)
; #pragma unroll
;                     for (int n = 0; n < 2; ++n) acc[a][b][m][n] = (f32x4){0.f, 0.f, 0.f, 0.f};
.LBB0_996:
	s_add_u32 s4, s50, 0x100
	v_mov_b32_e32 v0, 0
	s_addc_u32 s5, s51, 0
	s_mov_b32 s58, -2
	s_waitcnt lgkmcnt(0)
	v_mov_b32_e32 v1, v0
	v_mov_b32_e32 v2, v0
	v_mov_b32_e32 v3, v0
	v_mov_b32_e32 v4, v0
	v_mov_b32_e32 v5, v0
	v_mov_b32_e32 v6, v0
	v_mov_b32_e32 v7, v0
	v_mov_b32_e32 v8, v0
	v_mov_b32_e32 v9, v0
	v_mov_b32_e32 v10, v0
	v_mov_b32_e32 v11, v0
	v_mov_b32_e32 v12, v0
	v_mov_b32_e32 v13, v0
	v_mov_b32_e32 v14, v0
	v_mov_b32_e32 v15, v0
	v_mov_b32_e32 v16, v0
	v_mov_b32_e32 v17, v0
	v_mov_b32_e32 v18, v0
	v_mov_b32_e32 v19, v0
	v_mov_b32_e32 v20, v0
	v_mov_b32_e32 v21, v0
	v_mov_b32_e32 v22, v0
	v_mov_b32_e32 v23, v0
	v_mov_b32_e32 v24, v0
	v_mov_b32_e32 v25, v0
	v_mov_b32_e32 v26, v0
	v_mov_b32_e32 v27, v0
	v_mov_b32_e32 v28, v0
	v_mov_b32_e32 v29, v0
	v_mov_b32_e32 v30, v0
	v_mov_b32_e32 v31, v0
	v_mov_b32_e32 v64, v0
	v_mov_b32_e32 v65, v0
	v_mov_b32_e32 v66, v0
	v_mov_b32_e32 v67, v0
	v_mov_b32_e32 v68, v0
	v_mov_b32_e32 v69, v0
	v_mov_b32_e32 v70, v0
	v_mov_b32_e32 v71, v0
	v_mov_b32_e32 v72, v0
	v_mov_b32_e32 v73, v0
	v_mov_b32_e32 v74, v0
	v_mov_b32_e32 v75, v0
	v_mov_b32_e32 v76, v0
	v_mov_b32_e32 v77, v0
	v_mov_b32_e32 v78, v0
	v_mov_b32_e32 v79, v0
	s_waitcnt vmcnt(0)
	v_mov_b32_e32 v80, v0
	v_mov_b32_e32 v81, v0
	v_mov_b32_e32 v82, v0
	v_mov_b32_e32 v83, v0
	v_mov_b32_e32 v84, v0
	v_mov_b32_e32 v85, v0
	v_mov_b32_e32 v86, v0
	v_mov_b32_e32 v87, v0
	v_mov_b32_e32 v88, v0
	v_mov_b32_e32 v89, v0
	v_mov_b32_e32 v90, v0
	v_mov_b32_e32 v91, v0
	v_mov_b32_e32 v92, v0
	v_mov_b32_e32 v93, v0
	v_mov_b32_e32 v94, v0
	v_mov_b32_e32 v95, v0
	v_mov_b32_e32 v32, v0
	v_mov_b32_e32 v33, v0
	v_mov_b32_e32 v34, v0
	v_mov_b32_e32 v35, v0
	v_mov_b32_e32 v36, v0
	v_mov_b32_e32 v37, v0
	v_mov_b32_e32 v38, v0
	v_mov_b32_e32 v39, v0
	v_mov_b32_e32 v40, v0
	v_mov_b32_e32 v41, v0
	v_mov_b32_e32 v42, v0
	v_mov_b32_e32 v43, v0
	v_mov_b32_e32 v44, v0
	v_mov_b32_e32 v45, v0
	v_mov_b32_e32 v46, v0
	v_mov_b32_e32 v47, v0
	v_mov_b32_e32 v48, v0
	v_mov_b32_e32 v49, v0
	v_mov_b32_e32 v50, v0
	v_mov_b32_e32 v51, v0
	v_mov_b32_e32 v52, v0
	v_mov_b32_e32 v53, v0
	v_mov_b32_e32 v54, v0
	v_mov_b32_e32 v55, v0
	v_mov_b32_e32 v56, v0
	v_mov_b32_e32 v57, v0
	v_mov_b32_e32 v58, v0
	v_mov_b32_e32 v59, v0
	v_mov_b32_e32 v60, v0
	v_mov_b32_e32 v61, v0
	v_mov_b32_e32 v62, v0
	v_mov_b32_e32 v63, v0
	v_mov_b32_e32 v96, v0
	v_mov_b32_e32 v97, v0
	v_mov_b32_e32 v98, v0
	v_mov_b32_e32 v99, v0
	v_mov_b32_e32 v100, v0
	v_mov_b32_e32 v101, v0
	v_mov_b32_e32 v102, v0
	v_mov_b32_e32 v103, v0
	v_mov_b32_e32 v104, v0
	v_mov_b32_e32 v105, v0
	v_mov_b32_e32 v106, v0
	v_mov_b32_e32 v107, v0
	v_mov_b32_e32 v108, v0
	v_mov_b32_e32 v109, v0
	v_mov_b32_e32 v110, v0
	v_mov_b32_e32 v111, v0
	v_mov_b32_e32 v112, v0
	v_mov_b32_e32 v113, v0
	v_mov_b32_e32 v114, v0
	v_mov_b32_e32 v115, v0
	v_mov_b32_e32 v116, v0
	v_mov_b32_e32 v117, v0
	v_mov_b32_e32 v118, v0
	v_mov_b32_e32 v119, v0
	v_mov_b32_e32 v120, v0
	v_mov_b32_e32 v121, v0
	v_mov_b32_e32 v122, v0
	v_mov_b32_e32 v123, v0
	v_mov_b32_e32 v124, v0
	v_mov_b32_e32 v125, v0
	v_mov_b32_e32 v126, v0
	v_mov_b32_e32 v127, v0
	v_add_u32_e32 v172, 0x10000, v224
.LBB0_997:
	s_add_u32 s50, s48, 0x100
	s_addc_u32 s51, s49, 0
	s_add_i32 s59, 0, 0x10000
	s_cmp_eq_u32 s58, 40
	s_cselect_b32 s55, s43, s51
	s_cselect_b32 s54, s42, s50
	s_cselect_b32 s53, s47, s5
	s_cselect_b32 s52, s46, s4
	s_add_i32 s60, 0, 0x14000
	ds_read_b128 v[130:133], v172
	ds_read_b128 v[134:137], v172 offset:1024
	ds_read_b128 v[138:141], v172 offset:2048
	ds_read_b128 v[142:145], v172 offset:3072
	ds_read_b128 v[146:149], v172 offset:16384
	ds_read_b128 v[150:153], v172 offset:17408
	ds_read_b128 v[154:157], v172 offset:18432
	ds_read_b128 v[158:161], v172 offset:19456
	s_add_i32 m0, s9, 0xc000
	ds_read_b128 v[186:189], v225
	ds_read_b128 v[190:193], v225 offset:1024
	ds_read_b128 v[194:197], v225 offset:2048
	ds_read_b128 v[198:201], v225 offset:3072
	ds_read_b128 v[202:205], v225 offset:4096
	ds_read_b128 v[206:209], v225 offset:5120
	ds_read_b128 v[210:213], v225 offset:6144
	ds_read_b128 v[214:217], v225 offset:7168
	global_load_lds_dwordx4 v168, s[48:49]
	s_add_i32 m0, s9, 0xe000
	s_nop 0
	global_load_lds_dwordx4 v170, s[48:49]
	s_waitcnt vmcnt(8)
	s_waitcnt lgkmcnt(0)
	s_barrier
	s_setprio 1
	s_waitcnt lgkmcnt(0)
	v_mfma_f32_16x16x32_bf16 v[124:127], v[130:133], v[186:189], v[124:127]
	v_mfma_f32_16x16x32_bf16 v[120:123], v[138:141], v[186:189], v[120:123]
	v_mfma_f32_16x16x32_bf16 v[116:119], v[130:133], v[194:197], v[116:119]
	v_mfma_f32_16x16x32_bf16 v[112:115], v[138:141], v[194:197], v[112:115]
	v_mfma_f32_16x16x32_bf16 v[108:111], v[130:133], v[202:205], v[108:111]
	v_mfma_f32_16x16x32_bf16 v[104:107], v[138:141], v[202:205], v[104:107]
	v_mfma_f32_16x16x32_bf16 v[100:103], v[130:133], v[210:213], v[100:103]
	v_mfma_f32_16x16x32_bf16 v[96:99], v[138:141], v[210:213], v[96:99]
	v_mfma_f32_16x16x32_bf16 v[124:127], v[134:137], v[190:193], v[124:127]
	v_mfma_f32_16x16x32_bf16 v[120:123], v[142:145], v[190:193], v[120:123]
	v_mfma_f32_16x16x32_bf16 v[116:119], v[134:137], v[198:201], v[116:119]
	v_mfma_f32_16x16x32_bf16 v[112:115], v[142:145], v[198:201], v[112:115]
	v_mfma_f32_16x16x32_bf16 v[108:111], v[134:137], v[206:209], v[108:111]
	v_mfma_f32_16x16x32_bf16 v[104:107], v[142:145], v[206:209], v[104:107]
	v_mfma_f32_16x16x32_bf16 v[100:103], v[134:137], v[214:217], v[100:103]
	v_mfma_f32_16x16x32_bf16 v[96:99], v[142:145], v[214:217], v[96:99]
	s_setprio 0
	s_setprio 1
	v_mfma_f32_16x16x32_bf16 v[60:63], v[146:149], v[186:189], v[60:63]
	v_mfma_f32_16x16x32_bf16 v[56:59], v[154:157], v[186:189], v[56:59]
	v_mfma_f32_16x16x32_bf16 v[52:55], v[146:149], v[194:197], v[52:55]
	v_mfma_f32_16x16x32_bf16 v[48:51], v[154:157], v[194:197], v[48:51]
	v_mfma_f32_16x16x32_bf16 v[44:47], v[146:149], v[202:205], v[44:47]
	v_mfma_f32_16x16x32_bf16 v[40:43], v[154:157], v[202:205], v[40:43]
	v_mfma_f32_16x16x32_bf16 v[36:39], v[146:149], v[210:213], v[36:39]
	v_mfma_f32_16x16x32_bf16 v[32:35], v[154:157], v[210:213], v[32:35]
	v_mfma_f32_16x16x32_bf16 v[60:63], v[150:153], v[190:193], v[60:63]
	v_mfma_f32_16x16x32_bf16 v[56:59], v[158:161], v[190:193], v[56:59]
	v_mfma_f32_16x16x32_bf16 v[52:55], v[150:153], v[198:201], v[52:55]
	v_mfma_f32_16x16x32_bf16 v[48:51], v[158:161], v[198:201], v[48:51]
	v_mfma_f32_16x16x32_bf16 v[44:47], v[150:153], v[206:209], v[44:47]
	v_mfma_f32_16x16x32_bf16 v[40:43], v[158:161], v[206:209], v[40:43]
	v_mfma_f32_16x16x32_bf16 v[36:39], v[150:153], v[214:217], v[36:39]
	v_mfma_f32_16x16x32_bf16 v[32:35], v[158:161], v[214:217], v[32:35]
	s_setprio 0
	s_barrier
; #define PG8_STAGE(bufoff, gbase, voff) do { _Pragma("unroll") for (int _i = 0; _i < 2; ++_i) \
;         __builtin_amdgcn_global_load_lds((const unsigned*)((const char*)(gbase) + (voff)[_i]), (PG8_LAS unsigned*)(lds + (bufoff) + ldsw + _i * 8192), 16, 0, 0); } while (0)
; #define PG8_LDA(dst, b, h) do { _Pragma("unroll") for (int m = 0; m < 4; ++m) _Pragma("unroll") for (int k = 0; k < 2; ++k) dst[m][k] = *(const PG8_LAS bf16x8*)(lds + PG8_SA(b, h) + aoff + m * 2048 + k * 1024); } while (0)
; #define PG8_LDB(dst, b, h) do { _Pragma("unroll") for (int n = 0; n < 2; ++n) _Pragma("unroll") for (int k = 0; k < 2; ++k) dst[n][k] = *(const PG8_LAS bf16x8*)(lds + PG8_SB(b, h) + boff + n * 2048 + k * 1024); } while (0)
; #define PG8_MMA(ai, bj, At, Bt) do { __builtin_amdgcn_s_setprio(1); _Pragma("unroll") for (int m = 0; m < 4; ++m) _Pragma("unroll") for (int n = 0; n < 2; ++n) _Pragma("unroll") for (int k = 0; k < 2; ++k) \
;         acc[ai][bj][m][n] = mma16<F16>(Bt[n][k], At[m][k], acc[ai][bj][m][n]); __builtin_amdgcn_s_setprio(0); } while (0)
; #define PG8_WAIT_V(n) asm volatile("s_waitcnt vmcnt(" #n ")" ::: "memory")
; #define PG8_WAIT_L(n) asm volatile("s_waitcnt lgkmcnt(" #n ")" ::: "memory")
; #define PG8_BAR __builtin_amdgcn_s_barrier()
; #define PG8_SCHED __builtin_amdgcn_sched_barrier(0)
; template <class Epi, class Sched, bool ALIGN_EPI = false, bool SP2 = false, bool F16 = false>
; __device__ __forceinline__ void gemm_phase(PG8_LAS unsigned char* lds, const Gemm g, const Sched& S, const Epi& E) {
;     ...
;             PG8_LDA(At, 0, 1); PG8_STAGE(PG8_SB(0, 0), b2, voffB); PG8_STAGE(PG8_SB(0, 1), b2 + hstep, voffB); PG8_STAGE(PG8_SA(0, 0), a2, voffA);
;             PG8_WAIT_V(8); PG8_WAIT_L(0); PG8_BAR; PG8_MMA(1, 0, At, B0); PG8_MMA(1, 1, At, B1); PG8_BAR; PG8_SCHED;
;             PG8_LDB(B0, 1, 0); PG8_LDB(B1, 1, 1); PG8_SCHED; PG8_LDA(At, 1, 0); PG8_STAGE(PG8_SA(0, 1), a2 + hstep, voffA);
;             PG8_WAIT_V(8); PG8_WAIT_L(0); PG8_BAR; PG8_MMA(0, 0, At, B0); PG8_MMA(0, 1, At, B1); PG8_BAR; PG8_SCHED;
;             PG8_LDA(At, 1, 1); PG8_STAGE(PG8_SB(1, 0), b3, voffB); PG8_STAGE(PG8_SB(1, 1), b3 + hstep, voffB); PG8_STAGE(PG8_SA(1, 0), a3, voffA);
	s_add_u32 s98, s52, s16
	s_addc_u32 s99, s53, s17
	s_add_u32 s100, s54, s16
	s_addc_u32 s101, s55, s17
	s_add_i32 s48, s59, s8
	s_mov_b32 m0, s48
	ds_read_b128 v[186:189], v225 offset:16384
	ds_read_b128 v[190:193], v225 offset:17408
	ds_read_b128 v[194:197], v225 offset:18432
	ds_read_b128 v[198:201], v225 offset:19456
	ds_read_b128 v[202:205], v225 offset:20480
	ds_read_b128 v[206:209], v225 offset:21504
	ds_read_b128 v[210:213], v225 offset:22528
	ds_read_b128 v[214:217], v225 offset:23552
	global_load_lds_dwordx4 v128, s[52:53]
	s_add_i32 m0, s48, 0x2000
	s_add_u32 s48, s52, 0xb0000
	s_addc_u32 s49, s53, 0
	s_add_i32 s59, s60, s8
	global_load_lds_dwordx4 v162, s[52:53]
	s_mov_b32 m0, s59
	s_nop 0
	global_load_lds_dwordx4 v128, s[48:49]
	s_add_i32 m0, s59, 0x2000
	s_nop 0
	global_load_lds_dwordx4 v162, s[48:49]
	s_mov_b32 m0, s9
	s_nop 0
	global_load_lds_dwordx4 v166, s[54:55]
	s_mov_b32 m0, s10
	s_nop 0
	global_load_lds_dwordx4 v164, s[54:55]
	s_waitcnt vmcnt(8)
	s_waitcnt lgkmcnt(0)
	s_barrier
	s_setprio 1
	s_waitcnt lgkmcnt(0)
	v_mfma_f32_16x16x32_bf16 v[92:95], v[130:133], v[186:189], v[92:95]
	v_mfma_f32_16x16x32_bf16 v[88:91], v[138:141], v[186:189], v[88:91]
	v_mfma_f32_16x16x32_bf16 v[84:87], v[130:133], v[194:197], v[84:87]
	v_mfma_f32_16x16x32_bf16 v[80:83], v[138:141], v[194:197], v[80:83]
	v_mfma_f32_16x16x32_bf16 v[76:79], v[130:133], v[202:205], v[76:79]
	v_mfma_f32_16x16x32_bf16 v[72:75], v[138:141], v[202:205], v[72:75]
	v_mfma_f32_16x16x32_bf16 v[68:71], v[130:133], v[210:213], v[68:71]
	v_mfma_f32_16x16x32_bf16 v[64:67], v[138:141], v[210:213], v[64:67]
	v_mfma_f32_16x16x32_bf16 v[92:95], v[134:137], v[190:193], v[92:95]
	v_mfma_f32_16x16x32_bf16 v[88:91], v[142:145], v[190:193], v[88:91]
	v_mfma_f32_16x16x32_bf16 v[84:87], v[134:137], v[198:201], v[84:87]
	v_mfma_f32_16x16x32_bf16 v[80:83], v[142:145], v[198:201], v[80:83]
	v_mfma_f32_16x16x32_bf16 v[76:79], v[134:137], v[206:209], v[76:79]
	v_mfma_f32_16x16x32_bf16 v[72:75], v[142:145], v[206:209], v[72:75]
	v_mfma_f32_16x16x32_bf16 v[68:71], v[134:137], v[214:217], v[68:71]
	v_mfma_f32_16x16x32_bf16 v[64:67], v[142:145], v[214:217], v[64:67]
	s_setprio 0
	s_setprio 1
	v_mfma_f32_16x16x32_bf16 v[28:31], v[146:149], v[186:189], v[28:31]
	v_mfma_f32_16x16x32_bf16 v[24:27], v[154:157], v[186:189], v[24:27]
	v_mfma_f32_16x16x32_bf16 v[20:23], v[146:149], v[194:197], v[20:23]
	v_mfma_f32_16x16x32_bf16 v[16:19], v[154:157], v[194:197], v[16:19]
	v_mfma_f32_16x16x32_bf16 v[12:15], v[146:149], v[202:205], v[12:15]
	v_mfma_f32_16x16x32_bf16 v[8:11], v[154:157], v[202:205], v[8:11]
	v_mfma_f32_16x16x32_bf16 v[4:7], v[146:149], v[210:213], v[4:7]
	v_mfma_f32_16x16x32_bf16 v[0:3], v[154:157], v[210:213], v[0:3]
	v_mfma_f32_16x16x32_bf16 v[28:31], v[150:153], v[190:193], v[28:31]
	v_mfma_f32_16x16x32_bf16 v[24:27], v[158:161], v[190:193], v[24:27]
	v_mfma_f32_16x16x32_bf16 v[20:23], v[150:153], v[198:201], v[20:23]
	v_mfma_f32_16x16x32_bf16 v[16:19], v[158:161], v[198:201], v[16:19]
	v_mfma_f32_16x16x32_bf16 v[12:15], v[150:153], v[206:209], v[12:15]
	v_mfma_f32_16x16x32_bf16 v[8:11], v[158:161], v[206:209], v[8:11]
	v_mfma_f32_16x16x32_bf16 v[4:7], v[150:153], v[214:217], v[4:7]
	v_mfma_f32_16x16x32_bf16 v[0:3], v[158:161], v[214:217], v[0:3]
	s_setprio 0
	s_barrier
	s_add_i32 s59, 0, 0x18000
	s_add_i32 s60, 0, 0x1c000
	ds_read_b128 v[130:133], v172 offset:32768
	ds_read_b128 v[134:137], v172 offset:33792
	ds_read_b128 v[138:141], v172 offset:34816
	ds_read_b128 v[142:145], v172 offset:35840
	ds_read_b128 v[146:149], v172 offset:49152
	ds_read_b128 v[150:153], v172 offset:50176
	ds_read_b128 v[154:157], v172 offset:51200
	ds_read_b128 v[158:161], v172 offset:52224
	s_add_u32 s48, s54, 0xb0000
	s_addc_u32 s49, s55, 0
	s_mov_b32 m0, s11
	ds_read_b128 v[186:189], v225 offset:32768
	ds_read_b128 v[190:193], v225 offset:33792
	ds_read_b128 v[194:197], v225 offset:34816
	ds_read_b128 v[198:201], v225 offset:35840
	ds_read_b128 v[202:205], v225 offset:36864
	ds_read_b128 v[206:209], v225 offset:37888
	ds_read_b128 v[210:213], v225 offset:38912
	ds_read_b128 v[214:217], v225 offset:39936
	global_load_lds_dwordx4 v166, s[48:49]
	s_mov_b32 m0, s14
	s_nop 0
	global_load_lds_dwordx4 v164, s[48:49]
	s_waitcnt vmcnt(8)
	s_waitcnt lgkmcnt(0)
	s_barrier
; #define PG8_STAGE(bufoff, gbase, voff) do { _Pragma("unroll") for (int _i = 0; _i < 2; ++_i) \
;         __builtin_amdgcn_global_load_lds((const unsigned*)((const char*)(gbase) + (voff)[_i]), (PG8_LAS unsigned*)(lds + (bufoff) + ldsw + _i * 8192), 16, 0, 0); } while (0)
; #define PG8_LDA(dst, b, h) do { _Pragma("unroll") for (int m = 0; m < 4; ++m) _Pragma("unroll") for (int k = 0; k < 2; ++k) dst[m][k] = *(const PG8_LAS bf16x8*)(lds + PG8_SA(b, h) + aoff + m * 2048 + k * 1024); } while (0)
; #define PG8_MMA(ai, bj, At, Bt) do { __builtin_amdgcn_s_setprio(1); _Pragma("unroll") for (int m = 0; m < 4; ++m) _Pragma("unroll") for (int n = 0; n < 2; ++n) _Pragma("unroll") for (int k = 0; k < 2; ++k) \
;         acc[ai][bj][m][n] = mma16<F16>(Bt[n][k], At[m][k], acc[ai][bj][m][n]); __builtin_amdgcn_s_setprio(0); } while (0)
; #define PG8_WAIT_V(n) asm volatile("s_waitcnt vmcnt(" #n ")" ::: "memory")
; #define PG8_WAIT_L(n) asm volatile("s_waitcnt lgkmcnt(" #n ")" ::: "memory")
; #define PG8_BAR __builtin_amdgcn_s_barrier()
; #define PG8_SCHED __builtin_amdgcn_sched_barrier(0)
; template <class Epi, class Sched, bool ALIGN_EPI = false, bool SP2 = false, bool F16 = false>
; __device__ __forceinline__ void gemm_phase(PG8_LAS unsigned char* lds, const Gemm g, const Sched& S, const Epi& E) {
;     ...
;             PG8_WAIT_V(8); PG8_WAIT_L(0); PG8_BAR; PG8_MMA(0, 0, At, B0); PG8_MMA(0, 1, At, B1); PG8_BAR; PG8_SCHED;
;             PG8_LDA(At, 1, 1); PG8_STAGE(PG8_SB(1, 0), b3, voffB); PG8_STAGE(PG8_SB(1, 1), b3 + hstep, voffB); PG8_STAGE(PG8_SA(1, 0), a3, voffA);
;             PG8_WAIT_V(8); PG8_WAIT_L(0); PG8_BAR; PG8_MMA(1, 0, At, B0); PG8_MMA(1, 1, At, B1); PG8_BAR; PG8_SCHED;
	s_setprio 1
	s_waitcnt lgkmcnt(0)
	v_mfma_f32_16x16x32_bf16 v[124:127], v[130:133], v[186:189], v[124:127]
	v_mfma_f32_16x16x32_bf16 v[120:123], v[138:141], v[186:189], v[120:123]
	v_mfma_f32_16x16x32_bf16 v[116:119], v[130:133], v[194:197], v[116:119]
	v_mfma_f32_16x16x32_bf16 v[112:115], v[138:141], v[194:197], v[112:115]
	v_mfma_f32_16x16x32_bf16 v[108:111], v[130:133], v[202:205], v[108:111]
	v_mfma_f32_16x16x32_bf16 v[104:107], v[138:141], v[202:205], v[104:107]
	v_mfma_f32_16x16x32_bf16 v[100:103], v[130:133], v[210:213], v[100:103]
	v_mfma_f32_16x16x32_bf16 v[96:99], v[138:141], v[210:213], v[96:99]
	v_mfma_f32_16x16x32_bf16 v[124:127], v[134:137], v[190:193], v[124:127]
	v_mfma_f32_16x16x32_bf16 v[120:123], v[142:145], v[190:193], v[120:123]
	v_mfma_f32_16x16x32_bf16 v[116:119], v[134:137], v[198:201], v[116:119]
	v_mfma_f32_16x16x32_bf16 v[112:115], v[142:145], v[198:201], v[112:115]
	v_mfma_f32_16x16x32_bf16 v[108:111], v[134:137], v[206:209], v[108:111]
	v_mfma_f32_16x16x32_bf16 v[104:107], v[142:145], v[206:209], v[104:107]
	v_mfma_f32_16x16x32_bf16 v[100:103], v[134:137], v[214:217], v[100:103]
	v_mfma_f32_16x16x32_bf16 v[96:99], v[142:145], v[214:217], v[96:99]
	s_setprio 0
	s_setprio 1
	v_mfma_f32_16x16x32_bf16 v[60:63], v[146:149], v[186:189], v[60:63]
	v_mfma_f32_16x16x32_bf16 v[56:59], v[154:157], v[186:189], v[56:59]
	v_mfma_f32_16x16x32_bf16 v[52:55], v[146:149], v[194:197], v[52:55]
	v_mfma_f32_16x16x32_bf16 v[48:51], v[154:157], v[194:197], v[48:51]
	v_mfma_f32_16x16x32_bf16 v[44:47], v[146:149], v[202:205], v[44:47]
	v_mfma_f32_16x16x32_bf16 v[40:43], v[154:157], v[202:205], v[40:43]
	v_mfma_f32_16x16x32_bf16 v[36:39], v[146:149], v[210:213], v[36:39]
	v_mfma_f32_16x16x32_bf16 v[32:35], v[154:157], v[210:213], v[32:35]
	v_mfma_f32_16x16x32_bf16 v[60:63], v[150:153], v[190:193], v[60:63]
	v_mfma_f32_16x16x32_bf16 v[56:59], v[158:161], v[190:193], v[56:59]
	v_mfma_f32_16x16x32_bf16 v[52:55], v[150:153], v[198:201], v[52:55]
	v_mfma_f32_16x16x32_bf16 v[48:51], v[158:161], v[198:201], v[48:51]
	v_mfma_f32_16x16x32_bf16 v[44:47], v[150:153], v[206:209], v[44:47]
	v_mfma_f32_16x16x32_bf16 v[40:43], v[158:161], v[206:209], v[40:43]
	v_mfma_f32_16x16x32_bf16 v[36:39], v[150:153], v[214:217], v[36:39]
	v_mfma_f32_16x16x32_bf16 v[32:35], v[158:161], v[214:217], v[32:35]
	s_setprio 0
	s_barrier
	s_add_i32 s48, s59, s8
	s_mov_b32 m0, s48
	ds_read_b128 v[186:189], v225 offset:49152
	ds_read_b128 v[190:193], v225 offset:50176
	ds_read_b128 v[194:197], v225 offset:51200
	ds_read_b128 v[198:201], v225 offset:52224
	ds_read_b128 v[202:205], v225 offset:53248
	ds_read_b128 v[206:209], v225 offset:54272
	ds_read_b128 v[210:213], v225 offset:55296
	ds_read_b128 v[214:217], v225 offset:56320
	global_load_lds_dwordx4 v128, s[98:99]
	s_add_i32 m0, s48, 0x2000
	s_add_u32 s48, s52, 0xb0080
	s_addc_u32 s49, s53, 0
	s_add_i32 s52, s60, s8
	global_load_lds_dwordx4 v162, s[98:99]
	s_mov_b32 m0, s52
	s_nop 0
	global_load_lds_dwordx4 v128, s[48:49]
	s_add_i32 m0, s52, 0x2000
	s_nop 0
	global_load_lds_dwordx4 v162, s[48:49]
	s_mov_b32 m0, s29
	s_nop 0
	global_load_lds_dwordx4 v166, s[100:101]
	s_mov_b32 m0, s30
	s_nop 0
	global_load_lds_dwordx4 v164, s[100:101]
	s_waitcnt vmcnt(8)
	s_waitcnt lgkmcnt(0)
	s_barrier
	s_setprio 1
	s_waitcnt lgkmcnt(0)
	v_mfma_f32_16x16x32_bf16 v[92:95], v[130:133], v[186:189], v[92:95]
	v_mfma_f32_16x16x32_bf16 v[88:91], v[138:141], v[186:189], v[88:91]
	v_mfma_f32_16x16x32_bf16 v[84:87], v[130:133], v[194:197], v[84:87]
	v_mfma_f32_16x16x32_bf16 v[80:83], v[138:141], v[194:197], v[80:83]
	v_mfma_f32_16x16x32_bf16 v[76:79], v[130:133], v[202:205], v[76:79]
	v_mfma_f32_16x16x32_bf16 v[72:75], v[138:141], v[202:205], v[72:75]
	v_mfma_f32_16x16x32_bf16 v[68:71], v[130:133], v[210:213], v[68:71]
	v_mfma_f32_16x16x32_bf16 v[64:67], v[138:141], v[210:213], v[64:67]
	v_mfma_f32_16x16x32_bf16 v[92:95], v[134:137], v[190:193], v[92:95]
	v_mfma_f32_16x16x32_bf16 v[88:91], v[142:145], v[190:193], v[88:91]
	v_mfma_f32_16x16x32_bf16 v[84:87], v[134:137], v[198:201], v[84:87]
	v_mfma_f32_16x16x32_bf16 v[80:83], v[142:145], v[198:201], v[80:83]
	v_mfma_f32_16x16x32_bf16 v[76:79], v[134:137], v[206:209], v[76:79]
	v_mfma_f32_16x16x32_bf16 v[72:75], v[142:145], v[206:209], v[72:75]
	v_mfma_f32_16x16x32_bf16 v[68:71], v[134:137], v[214:217], v[68:71]
	v_mfma_f32_16x16x32_bf16 v[64:67], v[142:145], v[214:217], v[64:67]
	s_setprio 0
	s_setprio 1
	v_mfma_f32_16x16x32_bf16 v[28:31], v[146:149], v[186:189], v[28:31]
	v_mfma_f32_16x16x32_bf16 v[24:27], v[154:157], v[186:189], v[24:27]
	v_mfma_f32_16x16x32_bf16 v[20:23], v[146:149], v[194:197], v[20:23]
	v_mfma_f32_16x16x32_bf16 v[16:19], v[154:157], v[194:197], v[16:19]
	v_mfma_f32_16x16x32_bf16 v[12:15], v[146:149], v[202:205], v[12:15]
	v_mfma_f32_16x16x32_bf16 v[8:11], v[154:157], v[202:205], v[8:11]
	v_mfma_f32_16x16x32_bf16 v[4:7], v[146:149], v[210:213], v[4:7]
	v_mfma_f32_16x16x32_bf16 v[0:3], v[154:157], v[210:213], v[0:3]
	v_mfma_f32_16x16x32_bf16 v[28:31], v[150:153], v[190:193], v[28:31]
	v_mfma_f32_16x16x32_bf16 v[24:27], v[158:161], v[190:193], v[24:27]
	v_mfma_f32_16x16x32_bf16 v[20:23], v[150:153], v[198:201], v[20:23]
	v_mfma_f32_16x16x32_bf16 v[16:19], v[158:161], v[198:201], v[16:19]
	v_mfma_f32_16x16x32_bf16 v[12:15], v[150:153], v[206:209], v[12:15]
	v_mfma_f32_16x16x32_bf16 v[8:11], v[158:161], v[206:209], v[8:11]
	v_mfma_f32_16x16x32_bf16 v[4:7], v[150:153], v[214:217], v[4:7]
	v_mfma_f32_16x16x32_bf16 v[0:3], v[158:161], v[214:217], v[0:3]
	s_setprio 0
	s_barrier
	s_add_i32 s58, s58, 2
	s_add_u32 s4, s4, 0x100
	s_addc_u32 s5, s5, 0
	s_cmp_gt_u32 s58, 41
	s_mov_b64 s[48:49], s[50:51]
	s_cbranch_scc0 .LBB0_997
	s_and_b64 vcc, exec, s[44:45]
	s_cbranch_vccz .LBB0_1000
	s_barrier
